# LDS tiles re-laid out as 16x128B blocks with XOR swizzle: each LDS-DMA piece fetches 8 full cache lines (all 4 GEMMs)
# speedup vs baseline: 1.0099x; 1.0020x over previous
; #define PG8_STAGE(bufoff, gbase) do { _Pragma("unroll") for (int _i = 0; _i < 2; ++_i) \
;         __builtin_amdgcn_global_load_lds((const unsigned*)((const char*)(gbase) + voffA[_i]), (LAS unsigned*)(lds + (bufoff) + ldsw + _i * 8192), 16, 0, 0); } while (0)
; #define PG8_WAIT_V(n) asm volatile("s_waitcnt vmcnt(" #n ")" ::: "memory")
; #define PG8_BAR __builtin_amdgcn_s_barrier()
; template <class Epi, class Sched, bool FP8 = false>
; __device__ __forceinline__ void gemm_phase(LAS unsigned char* lds, const Gemm g, const Sched& S, const Epi& E, const int tid) {
;     const int wid = __builtin_amdgcn_readfirstlane(tid >> 6), lane = tid & 63, wr = wid >> 2, wc = wid & 3, fr = lane & 15, fq = lane >> 4;
;     const int K = g.K, nt = g.Kloop / BK;
;     const size_t halfb = (size_t)g.Kloop * 2;
;     const int sc8 = 0x7f7f7f7f;
;     unsigned voffA[2];
; #pragma unroll
;     for (int i = 0; i < 2; ++i) { int R, C; stage_rc(tid * 16 + i * 8192, R, C); voffA[i] = (unsigned)(R * K + C) * 2u; }
;     const size_t kstep = (size_t)(BK * 2);
;     const size_t hstep = (size_t)HALF * K * 2;
;     const size_t tstep = 2 * hstep;
;     const unsigned ldsw = (unsigned)wid * 1024u;
;     const int aoff = lds_byte(wr * 64 + fr, fq * 8), boff = lds_byte(wc * 32 + fr, fq * 8);
;     ...
;     Unit cur, nxt; int ui = 0;
;     if (!S.next(0, cur)) return;
;     f32x4 acc[2][2][4][2];
; #pragma unroll
;     for (int a = 0; a < 2; ++a)
; #pragma unroll
;         for (int b = 0; b < 2; ++b)
; #pragma unroll
;             for (int m = 0; m < 4; ++m)
; #pragma unroll
;                 for (int n = 0; n < 2; ++n) acc[a][b][m][n] = (f32x4){0.f, 0.f, 0.f, 0.f};
;     h16x8 At[4][2], B0[2][2], B1[2][2];
;     const char* cA = (const char*)g.A + (size_t)cur.pm * tstep + cur.half * halfb; const char* cB = (const char*)g.Bt + (size_t)cur.pn * tstep + cur.half * halfb;
;     PG8_STAGE(PG8_SB(0, 0), cB); PG8_STAGE(PG8_SB(0, 1), cB + hstep); PG8_STAGE(PG8_SA(0, 0), cA); PG8_STAGE(PG8_SA(0, 1), cA + hstep);
;     if (wr == 1) PG8_BAR;
;     PG8_WAIT_V(2); PG8_BAR;
;     PG8_STAGE(PG8_SB(1, 0), cB + kstep); PG8_STAGE(PG8_SA(1, 0), cA + kstep); PG8_STAGE(PG8_SB(1, 1), cB + hstep + kstep);
;     PG8_WAIT_V(6); PG8_BAR;
.LBB0_88:
	s_andn2_b64 vcc, exec, s[0:1]
	s_ashr_i32 s31, s30, 31
	s_cbranch_vccnz .LBB0_144
	v_ashrrev_i32_e32 v2, 31, v0
	v_lshrrev_b32_e32 v2, 26, v2
	v_lshlrev_b32_e32 v1, 4, v0
	v_add_u32_e32 v2, v0, v2
	v_bfe_i32 v0, v0, 27, 1
	v_lshrrev_b32_e32 v0, 22, v0
	v_add_u32_e32 v0, v1, v0
	v_and_b32_e32 v0, 0xfffffc00, v0
	v_sub_u32_e32 v0, v1, v0
	v_ashrrev_i32_e32 v9, 6, v2
	v_lshrrev_b32_e32 v2, 4, v0
	v_bitop3_b32 v0, v2, v0, 32 bitop3:0x6c
	v_ashrrev_i32_e32 v3, 31, v0
	v_lshrrev_b32_e32 v3, 26, v3
	v_add_u32_e32 v3, v0, v3
	v_ashrrev_i32_e32 v10, 6, v3
	v_and_b32_e32 v3, 0xc0, v3
	v_sub_u32_e32 v0, v0, v3
	v_mov_b32_e32 v3, 1
	v_lshlrev_b32_e32 v2, 3, v9
	v_lshlrev_b32_e32 v4, 5, v9
	v_ashrrev_i16_sdwa v0, v3, sext(v0) dst_sel:DWORD dst_unused:UNUSED_PAD src0_sel:DWORD src1_sel:BYTE_0
	v_and_b32_e32 v2, 0x7fff0, v2
	v_and_b32_e32 v4, 32, v4
	v_bfe_i32 v11, v0, 0, 16
	v_add_u32_e32 v0, v4, v11
	v_add_lshl_u32 v2, v10, v2, 13
	v_lshl_add_u32 v128, v0, 1, v2
	v_mbcnt_lo_u32_b32 v239, -1, 0
	v_mbcnt_hi_u32_b32 v239, -1, v239
	s_lshr_b32 s92, s33, 6
	s_lshl_b32 s93, s92, 3
	s_and_b32 s94, s92, 1
	s_lshl_b32 s94, s94, 2
	v_lshrrev_b32_e32 v236, 3, v239
	v_add_u32_e32 v236, s93, v236
	v_lshrrev_b32_e32 v237, 4, v239
	v_add_u32_e32 v237, s94, v237
	v_and_b32_e32 v238, 7, v239
	v_xor_b32_e32 v237, v238, v237
	v_lshlrev_b32_e32 v237, 4, v237
	v_lshl_add_u32 v128, v236, 13, v237
	v_add_u32_e32 v0, 0x2000, v1
	v_ashrrev_i32_e32 v1, 31, v0
	v_lshrrev_b32_e32 v1, 22, v1
	v_add_u32_e32 v1, v0, v1
	v_ashrrev_i32_e32 v12, 10, v1
	v_mul_i32_i24_e32 v1, 0x400, v12
	v_sub_u32_e32 v0, v0, v1
	v_lshrrev_b32_e32 v1, 4, v0
	s_add_u32 s54, s53, 0x200000
	v_bitop3_b32 v0, v1, v0, 32 bitop3:0x6c
	s_addc_u32 s55, s7, 0
	v_ashrrev_i32_e32 v2, 31, v0
	s_add_u32 s56, s53, 0x10200000
	v_lshrrev_b32_e32 v2, 26, v2
	s_addc_u32 s57, s7, 0
	s_ashr_i32 s0, s16, 6
	v_add_u32_e32 v2, v0, v2
	s_ashr_i32 s5, s4, 31
	s_ashr_i32 s19, s18, 31
	v_ashrrev_i32_e32 v13, 6, v2
	v_and_b32_e32 v2, 0xc0, v2
	s_ashr_i32 s1, s16, 8
	s_lshl_b32 s58, s0, 10
	s_lshl_b64 s[10:11], s[4:5], 21
	s_lshl_b64 s[12:13], s[18:19], 21
	v_sub_u32_e32 v0, v0, v2
	s_add_u32 s48, s54, s12
	v_lshlrev_b32_e32 v1, 3, v12
	v_lshlrev_b32_e32 v4, 5, v12
	v_ashrrev_i16_sdwa v0, v3, sext(v0) dst_sel:DWORD dst_unused:UNUSED_PAD src0_sel:DWORD src1_sel:BYTE_0
	s_addc_u32 s49, s55, s13
	s_add_i32 s19, s58, 0
	v_and_b32_e32 v1, 0x7fff0, v1
	v_and_b32_e32 v4, 32, v4
	v_bfe_i32 v14, v0, 0, 16
	s_add_i32 m0, s19, 0x10000
	v_add_u32_e32 v0, v4, v14
	v_add_lshl_u32 v1, v13, v1, 13
	global_load_lds_dwordx4 v128, s[48:49]
	s_add_i32 m0, s19, 0x12000
	v_lshl_add_u32 v130, v0, 1, v1
	v_add_u32_e32 v130, 0x80000, v128
	s_add_u32 s12, s48, 0x100000
	global_load_lds_dwordx4 v130, s[48:49]
	s_addc_u32 s13, s49, 0
	s_add_i32 m0, s19, 0x14000
	v_mov_b32_e32 v129, 0
	global_load_lds_dwordx4 v128, s[12:13]
	s_add_i32 m0, s19, 0x16000
	s_add_u32 s46, s56, s10
	s_addc_u32 s47, s57, s11
	s_add_i32 s59, s19, 0x2000
	global_load_lds_dwordx4 v130, s[12:13]
	s_mov_b32 m0, s19
	s_add_u32 s10, s46, 0x100000
	global_load_lds_dwordx4 v128, s[46:47]
	s_mov_b32 m0, s59
	s_addc_u32 s11, s47, 0
	s_add_i32 s60, s19, 0x4000
	global_load_lds_dwordx4 v130, s[46:47]
	s_mov_b32 m0, s60
	s_add_i32 s61, s19, 0x6000
	global_load_lds_dwordx4 v128, s[10:11]
	s_mov_b32 m0, s61
	v_mov_b32_e32 v131, v129
	global_load_lds_dwordx4 v130, s[10:11]
	s_cmp_eq_u32 s1, 1
	s_mov_b64 s[10:11], 0x200000
	s_mov_b32 s62, 0
	v_lshl_add_u64 v[6:7], s[48:49], 0, v[128:129]
	v_lshl_add_u64 v[4:5], s[48:49], 0, v[130:131]
	v_lshl_add_u64 v[0:1], s[46:47], 0, v[128:129]
	s_cselect_b64 s[12:13], -1, 0
	s_cmp_lg_u32 s1, 1
	v_lshl_add_u64 v[2:3], s[46:47], 0, v[130:131]
	s_cbranch_scc1 .LBB0_91
	s_barrier
.LBB0_91:
	s_add_u32 s5, s53, 0x14200000
	s_mov_b64 s[14:15], 0x80
	s_addc_u32 s22, s7, 0
	s_and_b32 s63, s0, 3
	s_add_i32 m0, s19, 0x18000
	v_lshl_add_u64 v[6:7], v[6:7], 0, s[14:15]
	s_lshl_b32 s0, s1, 13
	s_lshl_b32 s17, s63, 12
	s_waitcnt vmcnt(2)
	s_barrier
	global_load_lds_dwordx4 v[6:7], off
	v_lshl_add_u64 v[4:5], v[4:5], 0, s[14:15]
	s_add_i32 m0, s19, 0x1a000
	s_add_i32 s66, s19, 0x8000
	s_add_i32 s67, s19, 0xa000
	global_load_lds_dwordx4 v[4:5], off
	v_lshl_add_u64 v[0:1], v[0:1], 0, s[14:15]
	s_mov_b32 m0, s66
	s_add_u32 s20, s48, 0x100080
	global_load_lds_dwordx4 v[0:1], off
	v_lshl_add_u64 v[0:1], v[2:3], 0, s[14:15]
	s_mov_b32 m0, s67
	s_addc_u32 s21, s49, 0
	global_load_lds_dwordx4 v[0:1], off
	s_add_i32 m0, s19, 0x1c000
	v_lshl_add_u64 v[0:1], s[20:21], 0, v[128:129]
	global_load_lds_dwordx4 v[0:1], off
	v_lshl_add_u64 v[0:1], s[20:21], 0, v[130:131]
	s_add_i32 m0, s19, 0x1e000
	v_lshlrev_b32_e32 v2, 2, v8
	global_load_lds_dwordx4 v[0:1], off
	v_lshrrev_b32_e32 v0, 1, v8
	v_and_b32_e32 v159, 24, v0
	v_and_b32_e32 v1, 15, v8
	v_lshlrev_b32_e32 v0, 1, v159
	v_lshl_or_b32 v158, s1, 6, v1
	v_lshl_or_b32 v1, v1, 6, v0
	v_and_b32_e32 v2, 32, v2
	s_cmpk_lt_u32 s16, 0x100
	v_bitop3_b32 v3, v1, s0, v2 bitop3:0xde
	v_bitop3_b32 v160, v1, s17, v2 bitop3:0xde
	s_cselect_b64 s[16:17], -1, 0
	s_lshl_b32 s0, s63, 6
	s_add_u32 s0, s5, s0
	s_addc_u32 s1, s22, 0
	v_mov_b32_e32 v1, v129
	v_lshl_add_u64 v[132:133], s[0:1], 0, v[0:1]
	v_lshlrev_b32_e32 v0, 16, v9
	v_and_b32_e32 v0, 0xfffe0000, v0
	v_lshl_add_u32 v0, v10, 13, v0
	v_and_b32_e32 v1, 1, v9
	v_lshl_or_b32 v0, v1, 6, v0
	v_lshl_add_u32 v134, v11, 1, v0
	v_mov_b32_e32 v134, v128
	v_lshlrev_b32_e32 v0, 16, v12
	v_and_b32_e32 v0, 0xfffe0000, v0
	s_waitcnt vmcnt(6)
	v_lshl_add_u32 v0, v13, 13, v0
	v_and_b32_e32 v1, 1, v12
	v_lshl_or_b32 v0, v1, 6, v0
	s_add_i32 s68, 0, 0x10000
	s_add_i32 s69, 0, 0x14000
	v_mov_b32_e32 v135, v129
	v_lshl_add_u32 v136, v14, 1, v0
	v_mov_b32_e32 v136, v130
	v_mov_b32_e32 v137, v129
	v_mov_b64_e32 v[138:139], 0x800
	v_mov_b64_e32 v[140:141], 0x7ff
	v_add_u32_e32 v161, s68, v160
	v_add_u32_e32 v162, s69, v160
	v_add_u32_e32 v163, 0, v3
	v_mbcnt_lo_u32_b32 v239, -1, 0
	v_mbcnt_hi_u32_b32 v239, -1, v239
	s_lshr_b32 s92, s33, 6
	s_lshr_b32 s93, s92, 2
	s_lshl_b32 s93, s93, 13
	s_and_b32 s94, s92, 3
	s_lshl_b32 s94, s94, 12
	v_and_b32_e32 v236, 15, v239
	v_lshrrev_b32_e32 v237, 4, v239
	v_lshrrev_b32_e32 v238, 1, v236
	v_xor_b32_e32 v237, v237, v238
	v_lshlrev_b32_e32 v237, 4, v237
	v_lshl_add_u32 v236, v236, 7, v237
	v_add_u32_e32 v163, s93, v236
	v_xor_b32_e32 v232, 64, v163
	v_add_u32_e32 v160, s94, v236
	v_xor_b32_e32 v233, 64, v160
	v_add_u32_e32 v161, 0x10000, v160
	v_add_u32_e32 v234, 0x10000, v233
	v_add_u32_e32 v162, 0x14000, v160
	v_add_u32_e32 v235, 0x14000, v233
	s_mov_b32 s70, 0x24200000
	s_mov_b32 s71, 0x200000
	s_mov_b64 s[20:21], 0x240000
	s_mov_b32 s72, 0x240000
	s_mov_b64 s[22:23], 0x280000
	s_mov_b32 s73, 0x280000
	s_mov_b64 s[24:25], 0x2c0000
	s_barrier
	s_branch .LBB0_94

.LBB0_101:
	ds_read_b128 v[142:145], v161
	ds_read_b128 v[146:149], v234
	ds_read_b128 v[150:153], v161 offset:2048
	ds_read_b128 v[154:157], v234 offset:2048
	ds_read_b128 v[164:167], v162
	ds_read_b128 v[168:171], v235
	ds_read_b128 v[172:175], v162 offset:2048
	ds_read_b128 v[176:179], v235 offset:2048
	s_add_u32 s48, s46, 0xfff00080
	s_addc_u32 s49, s47, -1
	s_cmp_eq_u32 s77, 60
	s_cselect_b32 s51, s5, s49
	s_cselect_b32 s50, s29, s48
	s_cselect_b32 s49, s27, s76
	s_cselect_b32 s48, s74, s75
	v_lshl_add_u64 v[214:215], s[46:47], 0, v[134:135]
	s_add_i32 m0, s19, 0xc000
	ds_read_b128 v[180:183], v163
	ds_read_b128 v[184:187], v232
	ds_read_b128 v[188:191], v163 offset:2048
	ds_read_b128 v[192:195], v232 offset:2048
	ds_read_b128 v[196:199], v163 offset:4096
	ds_read_b128 v[200:203], v232 offset:4096
	ds_read_b128 v[204:207], v163 offset:6144
	ds_read_b128 v[208:211], v232 offset:6144
	global_load_lds_dwordx4 v[214:215], off
	v_lshl_add_u64 v[214:215], s[46:47], 0, v[136:137]
	s_add_i32 m0, s19, 0xe000
	s_nop 0
	global_load_lds_dwordx4 v[214:215], off
	s_waitcnt vmcnt(8)
	s_waitcnt lgkmcnt(0)
	s_barrier
	s_setprio 1
	s_waitcnt lgkmcnt(0)
	v_mfma_f32_16x16x32_bf16 v[124:127], v[142:145], v[180:183], v[124:127]
	v_mfma_f32_16x16x32_bf16 v[120:123], v[150:153], v[180:183], v[120:123]
	v_mfma_f32_16x16x32_bf16 v[116:119], v[142:145], v[188:191], v[116:119]
	v_mfma_f32_16x16x32_bf16 v[112:115], v[150:153], v[188:191], v[112:115]
	v_mfma_f32_16x16x32_bf16 v[100:103], v[142:145], v[196:199], v[100:103]
	v_mfma_f32_16x16x32_bf16 v[96:99], v[150:153], v[196:199], v[96:99]
	v_mfma_f32_16x16x32_bf16 v[84:87], v[142:145], v[204:207], v[84:87]
	v_mfma_f32_16x16x32_bf16 v[80:83], v[150:153], v[204:207], v[80:83]
	v_mfma_f32_16x16x32_bf16 v[124:127], v[146:149], v[184:187], v[124:127]
	v_mfma_f32_16x16x32_bf16 v[120:123], v[154:157], v[184:187], v[120:123]
	v_mfma_f32_16x16x32_bf16 v[116:119], v[146:149], v[192:195], v[116:119]
	v_mfma_f32_16x16x32_bf16 v[112:115], v[154:157], v[192:195], v[112:115]
	v_mfma_f32_16x16x32_bf16 v[100:103], v[146:149], v[200:203], v[100:103]
	v_mfma_f32_16x16x32_bf16 v[96:99], v[154:157], v[200:203], v[96:99]
	v_mfma_f32_16x16x32_bf16 v[84:87], v[146:149], v[208:211], v[84:87]
	v_mfma_f32_16x16x32_bf16 v[80:83], v[154:157], v[208:211], v[80:83]
	s_setprio 0
	s_setprio 1
	v_mfma_f32_16x16x32_bf16 v[108:111], v[164:167], v[180:183], v[108:111]
	v_mfma_f32_16x16x32_bf16 v[104:107], v[172:175], v[180:183], v[104:107]
	v_mfma_f32_16x16x32_bf16 v[92:95], v[164:167], v[188:191], v[92:95]
	v_mfma_f32_16x16x32_bf16 v[88:91], v[172:175], v[188:191], v[88:91]
	v_mfma_f32_16x16x32_bf16 v[76:79], v[164:167], v[196:199], v[76:79]
	v_mfma_f32_16x16x32_bf16 v[72:75], v[172:175], v[196:199], v[72:75]
	v_mfma_f32_16x16x32_bf16 v[68:71], v[164:167], v[204:207], v[68:71]
	v_mfma_f32_16x16x32_bf16 v[64:67], v[172:175], v[204:207], v[64:67]
	v_mfma_f32_16x16x32_bf16 v[108:111], v[168:171], v[184:187], v[108:111]
	v_mfma_f32_16x16x32_bf16 v[104:107], v[176:179], v[184:187], v[104:107]
	v_mfma_f32_16x16x32_bf16 v[92:95], v[168:171], v[192:195], v[92:95]
	v_mfma_f32_16x16x32_bf16 v[88:91], v[176:179], v[192:195], v[88:91]
	v_mfma_f32_16x16x32_bf16 v[76:79], v[168:171], v[200:203], v[76:79]
	v_mfma_f32_16x16x32_bf16 v[72:75], v[176:179], v[200:203], v[72:75]
	v_mfma_f32_16x16x32_bf16 v[68:71], v[168:171], v[208:211], v[68:71]
	v_mfma_f32_16x16x32_bf16 v[64:67], v[176:179], v[208:211], v[64:67]
	s_setprio 0
	s_barrier
	s_add_i32 s78, s68, s58
	v_lshl_add_u64 v[214:215], s[48:49], 0, v[128:129]
	s_mov_b32 m0, s78
	ds_read_b128 v[180:183], v163 offset:16384
	ds_read_b128 v[184:187], v232 offset:16384
	ds_read_b128 v[188:191], v163 offset:18432
	ds_read_b128 v[192:195], v232 offset:18432
	ds_read_b128 v[196:199], v163 offset:20480
	ds_read_b128 v[200:203], v232 offset:20480
	ds_read_b128 v[204:207], v163 offset:22528
	ds_read_b128 v[208:211], v232 offset:22528
	global_load_lds_dwordx4 v[214:215], off
	s_add_i32 m0, s78, 0x2000
	s_add_u32 s78, s48, 0x100000
	v_lshl_add_u64 v[216:217], s[48:49], 0, v[130:131]
	s_addc_u32 s79, s49, 0
	s_add_i32 s80, s69, s58
	global_load_lds_dwordx4 v[216:217], off
	v_lshl_add_u64 v[218:219], s[78:79], 0, v[128:129]
	s_mov_b32 m0, s80
	v_lshl_add_u64 v[220:221], s[50:51], 0, v[130:131]
	global_load_lds_dwordx4 v[218:219], off
	v_lshl_add_u64 v[218:219], s[78:79], 0, v[130:131]
	s_add_i32 m0, s80, 0x2000
	s_nop 0
	global_load_lds_dwordx4 v[218:219], off
	v_lshl_add_u64 v[218:219], s[50:51], 0, v[128:129]
	s_mov_b32 m0, s19
	s_nop 0
	global_load_lds_dwordx4 v[218:219], off
	s_mov_b32 m0, s59
	s_nop 0
	global_load_lds_dwordx4 v[220:221], off
	s_waitcnt vmcnt(8)
	s_waitcnt lgkmcnt(0)
	s_barrier
	s_setprio 1
	s_waitcnt lgkmcnt(0)
	v_mfma_f32_16x16x32_bf16 v[60:63], v[142:145], v[180:183], v[60:63]
	v_mfma_f32_16x16x32_bf16 v[56:59], v[150:153], v[180:183], v[56:59]
	v_mfma_f32_16x16x32_bf16 v[52:55], v[142:145], v[188:191], v[52:55]
	v_mfma_f32_16x16x32_bf16 v[48:51], v[150:153], v[188:191], v[48:51]
	v_mfma_f32_16x16x32_bf16 v[36:39], v[142:145], v[196:199], v[36:39]
	v_mfma_f32_16x16x32_bf16 v[32:35], v[150:153], v[196:199], v[32:35]
	v_mfma_f32_16x16x32_bf16 v[20:23], v[142:145], v[204:207], v[20:23]
	v_mfma_f32_16x16x32_bf16 v[16:19], v[150:153], v[204:207], v[16:19]
	v_mfma_f32_16x16x32_bf16 v[60:63], v[146:149], v[184:187], v[60:63]
	v_mfma_f32_16x16x32_bf16 v[56:59], v[154:157], v[184:187], v[56:59]
	v_mfma_f32_16x16x32_bf16 v[52:55], v[146:149], v[192:195], v[52:55]
	v_mfma_f32_16x16x32_bf16 v[48:51], v[154:157], v[192:195], v[48:51]
	v_mfma_f32_16x16x32_bf16 v[36:39], v[146:149], v[200:203], v[36:39]
	v_mfma_f32_16x16x32_bf16 v[32:35], v[154:157], v[200:203], v[32:35]
	v_mfma_f32_16x16x32_bf16 v[20:23], v[146:149], v[208:211], v[20:23]
	v_mfma_f32_16x16x32_bf16 v[16:19], v[154:157], v[208:211], v[16:19]
	s_setprio 0
	s_setprio 1
	v_mfma_f32_16x16x32_bf16 v[44:47], v[164:167], v[180:183], v[44:47]
	v_mfma_f32_16x16x32_bf16 v[40:43], v[172:175], v[180:183], v[40:43]
	v_mfma_f32_16x16x32_bf16 v[28:31], v[164:167], v[188:191], v[28:31]
	v_mfma_f32_16x16x32_bf16 v[24:27], v[172:175], v[188:191], v[24:27]
	v_mfma_f32_16x16x32_bf16 v[12:15], v[164:167], v[196:199], v[12:15]
	v_mfma_f32_16x16x32_bf16 v[8:11], v[172:175], v[196:199], v[8:11]
	v_mfma_f32_16x16x32_bf16 v[4:7], v[164:167], v[204:207], v[4:7]
	v_mfma_f32_16x16x32_bf16 v[0:3], v[172:175], v[204:207], v[0:3]
	v_mfma_f32_16x16x32_bf16 v[44:47], v[168:171], v[184:187], v[44:47]
	v_mfma_f32_16x16x32_bf16 v[40:43], v[176:179], v[184:187], v[40:43]
	v_mfma_f32_16x16x32_bf16 v[28:31], v[168:171], v[192:195], v[28:31]
	v_mfma_f32_16x16x32_bf16 v[24:27], v[176:179], v[192:195], v[24:27]
	v_mfma_f32_16x16x32_bf16 v[12:15], v[168:171], v[200:203], v[12:15]
	v_mfma_f32_16x16x32_bf16 v[8:11], v[176:179], v[200:203], v[8:11]
	v_mfma_f32_16x16x32_bf16 v[4:7], v[168:171], v[208:211], v[4:7]
	v_mfma_f32_16x16x32_bf16 v[0:3], v[176:179], v[208:211], v[0:3]
	s_setprio 0
	s_barrier
	s_add_i32 s78, 0, 0x18000
	s_add_i32 s79, 0, 0x1c000
	v_add_u32_e32 v154, s78, v160
	v_add_u32_e32 v230, s78, v233
	v_add_u32_e32 v176, s79, v160
	v_add_u32_e32 v231, s79, v233
	ds_read_b128 v[142:145], v154
	ds_read_b128 v[146:149], v230
	ds_read_b128 v[150:153], v154 offset:2048
	ds_read_b128 v[154:157], v230 offset:2048
	ds_read_b128 v[164:167], v176
	ds_read_b128 v[168:171], v231
	ds_read_b128 v[172:175], v176 offset:2048
	ds_read_b128 v[176:179], v231 offset:2048
	s_add_u32 s50, s50, 0x100000
	s_addc_u32 s51, s51, 0
	s_mov_b32 m0, s60
	v_lshl_add_u64 v[222:223], s[50:51], 0, v[128:129]
	ds_read_b128 v[180:183], v163 offset:32768
	ds_read_b128 v[184:187], v232 offset:32768
	ds_read_b128 v[188:191], v163 offset:34816
	ds_read_b128 v[192:195], v232 offset:34816
	ds_read_b128 v[196:199], v163 offset:36864
	ds_read_b128 v[200:203], v232 offset:36864
	ds_read_b128 v[204:207], v163 offset:38912
	ds_read_b128 v[208:211], v232 offset:38912
	global_load_lds_dwordx4 v[222:223], off
	v_lshl_add_u64 v[222:223], s[50:51], 0, v[130:131]
	s_mov_b32 m0, s61
	s_nop 0
	global_load_lds_dwordx4 v[222:223], off
	s_waitcnt vmcnt(8)
	s_waitcnt lgkmcnt(0)
	s_barrier
	s_setprio 1
	s_waitcnt lgkmcnt(0)
	v_mfma_f32_16x16x32_bf16 v[124:127], v[142:145], v[180:183], v[124:127]
	v_mfma_f32_16x16x32_bf16 v[120:123], v[150:153], v[180:183], v[120:123]
	v_mfma_f32_16x16x32_bf16 v[116:119], v[142:145], v[188:191], v[116:119]
	v_mfma_f32_16x16x32_bf16 v[112:115], v[150:153], v[188:191], v[112:115]
	v_mfma_f32_16x16x32_bf16 v[100:103], v[142:145], v[196:199], v[100:103]
	v_mfma_f32_16x16x32_bf16 v[96:99], v[150:153], v[196:199], v[96:99]
	v_mfma_f32_16x16x32_bf16 v[84:87], v[142:145], v[204:207], v[84:87]
	v_mfma_f32_16x16x32_bf16 v[80:83], v[150:153], v[204:207], v[80:83]
	v_mfma_f32_16x16x32_bf16 v[124:127], v[146:149], v[184:187], v[124:127]
	v_mfma_f32_16x16x32_bf16 v[120:123], v[154:157], v[184:187], v[120:123]
	v_mfma_f32_16x16x32_bf16 v[116:119], v[146:149], v[192:195], v[116:119]
	v_mfma_f32_16x16x32_bf16 v[112:115], v[154:157], v[192:195], v[112:115]
	v_mfma_f32_16x16x32_bf16 v[100:103], v[146:149], v[200:203], v[100:103]
	v_mfma_f32_16x16x32_bf16 v[96:99], v[154:157], v[200:203], v[96:99]
	v_mfma_f32_16x16x32_bf16 v[84:87], v[146:149], v[208:211], v[84:87]
	v_mfma_f32_16x16x32_bf16 v[80:83], v[154:157], v[208:211], v[80:83]
	s_setprio 0
	s_setprio 1
	v_mfma_f32_16x16x32_bf16 v[108:111], v[164:167], v[180:183], v[108:111]
	v_mfma_f32_16x16x32_bf16 v[104:107], v[172:175], v[180:183], v[104:107]
	v_mfma_f32_16x16x32_bf16 v[92:95], v[164:167], v[188:191], v[92:95]
	v_mfma_f32_16x16x32_bf16 v[88:91], v[172:175], v[188:191], v[88:91]
	v_mfma_f32_16x16x32_bf16 v[76:79], v[164:167], v[196:199], v[76:79]
	v_mfma_f32_16x16x32_bf16 v[72:75], v[172:175], v[196:199], v[72:75]
	v_mfma_f32_16x16x32_bf16 v[68:71], v[164:167], v[204:207], v[68:71]
	v_mfma_f32_16x16x32_bf16 v[64:67], v[172:175], v[204:207], v[64:67]
	v_mfma_f32_16x16x32_bf16 v[108:111], v[168:171], v[184:187], v[108:111]
	v_mfma_f32_16x16x32_bf16 v[104:107], v[176:179], v[184:187], v[104:107]
	v_mfma_f32_16x16x32_bf16 v[92:95], v[168:171], v[192:195], v[92:95]
	v_mfma_f32_16x16x32_bf16 v[88:91], v[176:179], v[192:195], v[88:91]
	v_mfma_f32_16x16x32_bf16 v[76:79], v[168:171], v[200:203], v[76:79]
	v_mfma_f32_16x16x32_bf16 v[72:75], v[176:179], v[200:203], v[72:75]
	v_mfma_f32_16x16x32_bf16 v[68:71], v[168:171], v[208:211], v[68:71]
	v_mfma_f32_16x16x32_bf16 v[64:67], v[176:179], v[208:211], v[64:67]
	s_setprio 0
	s_barrier
; template <class Epi, class Sched, bool FP8 = false>
; __device__ __forceinline__ void gemm_phase(LAS unsigned char* lds, const Gemm g, const Sched& S, const Epi& E, const int tid) {
;     ...
;         for (int t = 0; t < nt; t += 2) PG8_KBODY(t);
	s_add_i32 s50, s78, s58
	v_lshl_add_u64 v[214:215], v[214:215], 0, s[14:15]
	s_mov_b32 m0, s50
	ds_read_b128 v[180:183], v163 offset:49152
	ds_read_b128 v[184:187], v232 offset:49152
	ds_read_b128 v[188:191], v163 offset:51200
	ds_read_b128 v[192:195], v232 offset:51200
	ds_read_b128 v[196:199], v163 offset:53248
	ds_read_b128 v[200:203], v232 offset:53248
	ds_read_b128 v[204:207], v163 offset:55296
	ds_read_b128 v[208:211], v232 offset:55296
	global_load_lds_dwordx4 v[214:215], off
	s_add_i32 m0, s50, 0x2000
	s_add_u32 s48, s48, 0x100080
	v_lshl_add_u64 v[214:215], v[216:217], 0, s[14:15]
	s_addc_u32 s49, s49, 0
	s_add_i32 s50, s79, s58
	global_load_lds_dwordx4 v[214:215], off
	v_lshl_add_u64 v[214:215], s[48:49], 0, v[128:129]
	s_mov_b32 m0, s50
	s_nop 0
	global_load_lds_dwordx4 v[214:215], off
	v_lshl_add_u64 v[214:215], s[48:49], 0, v[130:131]
	s_add_i32 m0, s50, 0x2000
	s_nop 0
	global_load_lds_dwordx4 v[214:215], off
	v_lshl_add_u64 v[214:215], v[218:219], 0, s[14:15]
	s_mov_b32 m0, s66
	s_nop 0
	global_load_lds_dwordx4 v[214:215], off
	v_lshl_add_u64 v[214:215], v[220:221], 0, s[14:15]
	s_mov_b32 m0, s67
	s_nop 0
	global_load_lds_dwordx4 v[214:215], off
	s_waitcnt vmcnt(8)
	s_waitcnt lgkmcnt(0)
	s_barrier
	s_setprio 1
	s_waitcnt lgkmcnt(0)
	v_mfma_f32_16x16x32_bf16 v[60:63], v[142:145], v[180:183], v[60:63]
	v_mfma_f32_16x16x32_bf16 v[56:59], v[150:153], v[180:183], v[56:59]
	v_mfma_f32_16x16x32_bf16 v[52:55], v[142:145], v[188:191], v[52:55]
	v_mfma_f32_16x16x32_bf16 v[48:51], v[150:153], v[188:191], v[48:51]
	v_mfma_f32_16x16x32_bf16 v[36:39], v[142:145], v[196:199], v[36:39]
	v_mfma_f32_16x16x32_bf16 v[32:35], v[150:153], v[196:199], v[32:35]
	v_mfma_f32_16x16x32_bf16 v[20:23], v[142:145], v[204:207], v[20:23]
	v_mfma_f32_16x16x32_bf16 v[16:19], v[150:153], v[204:207], v[16:19]
	v_mfma_f32_16x16x32_bf16 v[60:63], v[146:149], v[184:187], v[60:63]
	v_mfma_f32_16x16x32_bf16 v[56:59], v[154:157], v[184:187], v[56:59]
	v_mfma_f32_16x16x32_bf16 v[52:55], v[146:149], v[192:195], v[52:55]
	v_mfma_f32_16x16x32_bf16 v[48:51], v[154:157], v[192:195], v[48:51]
	v_mfma_f32_16x16x32_bf16 v[36:39], v[146:149], v[200:203], v[36:39]
	v_mfma_f32_16x16x32_bf16 v[32:35], v[154:157], v[200:203], v[32:35]
	v_mfma_f32_16x16x32_bf16 v[20:23], v[146:149], v[208:211], v[20:23]
	v_mfma_f32_16x16x32_bf16 v[16:19], v[154:157], v[208:211], v[16:19]
	s_setprio 0
	s_setprio 1
	v_mfma_f32_16x16x32_bf16 v[44:47], v[164:167], v[180:183], v[44:47]
	v_mfma_f32_16x16x32_bf16 v[40:43], v[172:175], v[180:183], v[40:43]
	v_mfma_f32_16x16x32_bf16 v[28:31], v[164:167], v[188:191], v[28:31]
	v_mfma_f32_16x16x32_bf16 v[24:27], v[172:175], v[188:191], v[24:27]
	v_mfma_f32_16x16x32_bf16 v[12:15], v[164:167], v[196:199], v[12:15]
	v_mfma_f32_16x16x32_bf16 v[8:11], v[172:175], v[196:199], v[8:11]
	v_mfma_f32_16x16x32_bf16 v[4:7], v[164:167], v[204:207], v[4:7]
	v_mfma_f32_16x16x32_bf16 v[0:3], v[172:175], v[204:207], v[0:3]
	v_mfma_f32_16x16x32_bf16 v[44:47], v[168:171], v[184:187], v[44:47]
	v_mfma_f32_16x16x32_bf16 v[40:43], v[176:179], v[184:187], v[40:43]
	v_mfma_f32_16x16x32_bf16 v[28:31], v[168:171], v[192:195], v[28:31]
	v_mfma_f32_16x16x32_bf16 v[24:27], v[176:179], v[192:195], v[24:27]
	v_mfma_f32_16x16x32_bf16 v[12:15], v[168:171], v[200:203], v[12:15]
	v_mfma_f32_16x16x32_bf16 v[8:11], v[176:179], v[200:203], v[8:11]
	v_mfma_f32_16x16x32_bf16 v[4:7], v[168:171], v[208:211], v[4:7]
	v_mfma_f32_16x16x32_bf16 v[0:3], v[176:179], v[208:211], v[0:3]
	s_setprio 0
	s_barrier
	s_add_i32 s77, s77, 2
	s_add_u32 s46, s46, 0x100
	s_addc_u32 s47, s47, 0
	s_add_u32 s75, s75, 0x100
	s_addc_u32 s76, s76, 0
	s_cmp_gt_u32 s77, 61
	s_cbranch_scc0 .LBB0_101
	s_and_b64 vcc, exec, s[16:17]
	s_cbranch_vccz .LBB0_104
	s_barrier

; #define PG8_STAGE(bufoff, gbase) do { _Pragma("unroll") for (int _i = 0; _i < 2; ++_i) \
;         __builtin_amdgcn_global_load_lds((const unsigned*)((const char*)(gbase) + voffA[_i]), (LAS unsigned*)(lds + (bufoff) + ldsw + _i * 8192), 16, 0, 0); } while (0)
; #define PG8_WAIT_V(n) asm volatile("s_waitcnt vmcnt(" #n ")" ::: "memory")
; #define PG8_BAR __builtin_amdgcn_s_barrier()
; template <class Epi, class Sched, bool FP8 = false>
; __device__ __forceinline__ void gemm_phase(LAS unsigned char* lds, const Gemm g, const Sched& S, const Epi& E, const int tid) {
;     const int wid = __builtin_amdgcn_readfirstlane(tid >> 6), lane = tid & 63, wr = wid >> 2, wc = wid & 3, fr = lane & 15, fq = lane >> 4;
;     const int K = g.K, nt = g.Kloop / BK;
;     const size_t halfb = (size_t)g.Kloop * 2;
;     const int sc8 = 0x7f7f7f7f;
;     unsigned voffA[2];
; #pragma unroll
;     for (int i = 0; i < 2; ++i) { int R, C; stage_rc(tid * 16 + i * 8192, R, C); voffA[i] = (unsigned)(R * K + C) * 2u; }
;     const size_t kstep = (size_t)(BK * 2);
;     const size_t hstep = (size_t)HALF * K * 2;
;     const size_t tstep = 2 * hstep;
;     const unsigned ldsw = (unsigned)wid * 1024u;
;     const int aoff = lds_byte(wr * 64 + fr, fq * 8), boff = lds_byte(wc * 32 + fr, fq * 8);
;     ...
;     Unit cur, nxt; int ui = 0;
;     if (!S.next(0, cur)) return;
;     f32x4 acc[2][2][4][2];
; #pragma unroll
;     for (int a = 0; a < 2; ++a)
; #pragma unroll
;         for (int b = 0; b < 2; ++b)
; #pragma unroll
;             for (int m = 0; m < 4; ++m)
; #pragma unroll
;                 for (int n = 0; n < 2; ++n) acc[a][b][m][n] = (f32x4){0.f, 0.f, 0.f, 0.f};
;     h16x8 At[4][2], B0[2][2], B1[2][2];
;     const char* cA = (const char*)g.A + (size_t)cur.pm * tstep + cur.half * halfb; const char* cB = (const char*)g.Bt + (size_t)cur.pn * tstep + cur.half * halfb;
;     PG8_STAGE(PG8_SB(0, 0), cB); PG8_STAGE(PG8_SB(0, 1), cB + hstep); PG8_STAGE(PG8_SA(0, 0), cA); PG8_STAGE(PG8_SA(0, 1), cA + hstep);
;     if (wr == 1) PG8_BAR;
;     PG8_WAIT_V(2); PG8_BAR;
;     PG8_STAGE(PG8_SB(1, 0), cB + kstep); PG8_STAGE(PG8_SA(1, 0), cA + kstep); PG8_STAGE(PG8_SB(1, 1), cB + hstep + kstep);
;     PG8_WAIT_V(6); PG8_BAR;
.LBB0_144:
	v_mbcnt_lo_u32_b32 v11, -1, 0
	v_mbcnt_hi_u32_b32 v11, -1, v11
	s_cmpk_gt_i32 s2, 0x3ff
	v_or_b32_e32 v0, s33, v11
	s_nop 0
	v_readfirstlane_b32 s12, v0
	s_cbranch_scc1 .LBB0_164
	v_lshlrev_b32_e32 v1, 4, v0
	v_add_u32_e32 v2, 0x2000, v1
	v_ashrrev_i32_e32 v3, 31, v2
	v_lshrrev_b32_e32 v3, 22, v3
	v_add_u32_e32 v3, v2, v3
	v_ashrrev_i32_e32 v8, 10, v3
	v_mul_i32_i24_e32 v4, 0x400, v8
	v_sub_u32_e32 v2, v2, v4
	v_lshrrev_b32_e32 v4, 4, v2
	v_bitop3_b32 v2, v4, v2, 32 bitop3:0x6c
	v_ashrrev_i32_e32 v4, 31, v2
	v_lshrrev_b32_e32 v4, 26, v4
	s_ashr_i32 s10, s12, 6
	v_add_u32_e32 v4, v2, v4
	s_ashr_i32 s1, s12, 8
	s_lshl_b32 s46, s10, 10
	s_lshl_b32 s0, s65, 7
	v_ashrrev_i32_e32 v9, 6, v4
	v_and_b32_e32 v4, 0xc0, v4
	s_add_u32 s47, s53, 0x38200000
	v_sub_u32_e32 v2, v2, v4
	v_mov_b32_e32 v4, 1
	s_addc_u32 s48, s7, 0
	v_lshlrev_b32_e32 v3, 5, v8
	v_ashrrev_i16_sdwa v2, v4, sext(v2) dst_sel:DWORD dst_unused:UNUSED_PAD src0_sel:DWORD src1_sel:BYTE_0
	s_add_u32 s49, s53, 0x3a200000
	v_and_b32_e32 v3, 32, v3
	v_bfe_i32 v10, v2, 0, 16
	s_addc_u32 s50, s7, 0
	v_add_u32_e32 v2, v3, v10
	v_lshlrev_b32_e32 v3, 3, v8
	s_mul_i32 s11, s65, 0x81
	v_and_b32_e32 v3, 0xffff0, v3
	s_and_b64 s[4:5], s[40:41], exec
	v_add_lshl_u32 v3, v9, v3, 12
	s_cselect_b32 s0, s11, s0
	v_lshl_add_u32 v160, v2, 1, v3
	v_ashrrev_i32_e32 v2, 31, v0
	s_add_i32 s0, s0, s64
	v_lshrrev_b32_e32 v2, 26, v2
	s_ashr_i32 s4, s0, 31
	v_add_u32_e32 v2, v0, v2
	v_bfe_i32 v0, v0, 27, 1
	s_lshr_b32 s4, s4, 25
	v_lshrrev_b32_e32 v0, 22, v0
	s_add_i32 s4, s0, s4
	v_add_u32_e32 v0, v1, v0
	s_ashr_i32 s5, s4, 7
	s_and_b32 s4, s4, 0xff80
	v_and_b32_e32 v0, 0xfffffc00, v0
	s_sub_i32 s4, s0, s4
	v_sub_u32_e32 v0, v1, v0
	s_bfe_i32 s0, s4, 0x80000
	v_lshrrev_b32_e32 v1, 4, v0
	s_bfe_u32 s0, s0, 0x2000d
	v_bitop3_b32 v0, v1, v0, 32 bitop3:0x6c
	s_add_i32 s11, s4, s0
	v_ashrrev_i32_e32 v1, 31, v0
	s_bfe_i32 s0, s11, 0x80000
	s_and_b32 s11, s11, 0xfc
	v_lshrrev_b32_e32 v1, 26, v1
	s_sub_i32 s4, s4, s11
	v_add_u32_e32 v1, v0, v1
	s_lshl_b32 s5, s5, 2
	s_sext_i32_i16 s0, s0
	s_sext_i32_i8 s4, s4
	v_ashrrev_i32_e32 v13, 6, v1
	v_and_b32_e32 v1, 0xc0, v1
	s_lshr_b32 s0, s0, 2
	s_add_i32 s26, s5, s4
	v_ashrrev_i32_e32 v12, 6, v2
	v_sub_u32_e32 v0, v0, v1
	s_ashr_i32 s27, s26, 31
	s_bfe_i64 s[14:15], s[0:1], 0x100000
	v_lshlrev_b32_e32 v2, 5, v12
	v_ashrrev_i16_sdwa v0, v4, sext(v0) dst_sel:DWORD dst_unused:UNUSED_PAD src0_sel:DWORD src1_sel:BYTE_0
	v_lshlrev_b32_e32 v1, 3, v12
	s_lshl_b64 s[4:5], s[26:27], 20
	s_lshl_b64 s[14:15], s[14:15], 20
	v_and_b32_e32 v2, 32, v2
	v_bfe_i32 v14, v0, 0, 16
	v_and_b32_e32 v1, 0xffff0, v1
	s_add_u32 s42, s49, s14
	v_add_u32_e32 v0, v2, v14
	v_add_lshl_u32 v1, v13, v1, 12
	s_addc_u32 s43, s50, s15
	s_add_i32 s51, s46, 0
	v_lshl_add_u32 v162, v0, 1, v1
	v_mbcnt_lo_u32_b32 v239, -1, 0
	v_mbcnt_hi_u32_b32 v239, -1, v239
	s_lshr_b32 s92, s33, 6
	s_lshl_b32 s93, s92, 3
	s_and_b32 s94, s92, 1
	s_lshl_b32 s94, s94, 2
	v_lshrrev_b32_e32 v236, 3, v239
	v_add_u32_e32 v236, s93, v236
	v_lshrrev_b32_e32 v237, 4, v239
	v_add_u32_e32 v237, s94, v237
	v_and_b32_e32 v238, 7, v239
	v_xor_b32_e32 v237, v238, v237
	v_lshlrev_b32_e32 v237, 4, v237
	v_lshl_add_u32 v162, v236, 12, v237
	v_add_u32_e32 v160, 0x40000, v162
	s_add_i32 m0, s51, 0x10000
	v_mov_b32_e32 v165, 0
	global_load_lds_dwordx4 v162, s[42:43]
	s_add_i32 m0, s51, 0x12000
	s_add_u32 s14, s42, 0x80000
	global_load_lds_dwordx4 v160, s[42:43]
	s_addc_u32 s15, s43, 0
	s_add_i32 m0, s51, 0x14000
	v_mov_b32_e32 v163, v165
	global_load_lds_dwordx4 v162, s[14:15]
	s_add_i32 m0, s51, 0x16000
	s_add_u32 s28, s47, s4
	s_addc_u32 s29, s48, s5
	s_add_i32 s54, s51, 0x2000
	global_load_lds_dwordx4 v160, s[14:15]
	s_mov_b32 m0, s51
	s_add_u32 s4, s28, 0x80000
	global_load_lds_dwordx4 v162, s[28:29]
	s_mov_b32 m0, s54
	s_addc_u32 s5, s29, 0
	s_add_i32 s55, s51, 0x4000
	global_load_lds_dwordx4 v160, s[28:29]
	s_mov_b32 m0, s55
	s_add_i32 s56, s51, 0x6000
	global_load_lds_dwordx4 v162, s[4:5]
	s_mov_b32 m0, s56
	v_mov_b32_e32 v161, v165
	global_load_lds_dwordx4 v160, s[4:5]
	s_cmp_eq_u32 s1, 1
	s_movk_i32 s57, 0x2000
	s_mov_b32 s58, 0
	s_mov_b32 s59, 0x10000
	v_lshl_add_u64 v[6:7], s[42:43], 0, v[162:163]
	v_lshl_add_u64 v[4:5], s[42:43], 0, v[160:161]
	s_mov_b32 s60, 0x12000
	s_mov_b32 s61, 0x14000
	s_mov_b32 s62, 0x16000
	v_lshl_add_u64 v[2:3], s[28:29], 0, v[162:163]
	v_lshl_add_u64 v[0:1], s[28:29], 0, v[160:161]
	s_movk_i32 s63, 0x4000
	s_cselect_b64 s[4:5], -1, 0
	s_cmp_lg_u32 s1, 1
	s_movk_i32 s66, 0x6000
	s_cbranch_scc1 .LBB0_147
	s_barrier
; #define PG8_STAGE(bufoff, gbase) do { _Pragma("unroll") for (int _i = 0; _i < 2; ++_i) \
;         __builtin_amdgcn_global_load_lds((const unsigned*)((const char*)(gbase) + voffA[_i]), (LAS unsigned*)(lds + (bufoff) + ldsw + _i * 8192), 16, 0, 0); } while (0)
; #define PG8_WAIT_V(n) asm volatile("s_waitcnt vmcnt(" #n ")" ::: "memory")
; #define PG8_BAR __builtin_amdgcn_s_barrier()
; template <class Epi, class Sched, bool FP8 = false>
; __device__ __forceinline__ void gemm_phase(LAS unsigned char* lds, const Gemm g, const Sched& S, const Epi& E, const int tid) {
;     const int wid = __builtin_amdgcn_readfirstlane(tid >> 6), lane = tid & 63, wr = wid >> 2, wc = wid & 3, fr = lane & 15, fq = lane >> 4;
;     const int K = g.K, nt = g.Kloop / BK;
;     const size_t halfb = (size_t)g.Kloop * 2;
;     const int sc8 = 0x7f7f7f7f;
;     unsigned voffA[2];
; #pragma unroll
;     for (int i = 0; i < 2; ++i) { int R, C; stage_rc(tid * 16 + i * 8192, R, C); voffA[i] = (unsigned)(R * K + C) * 2u; }
;     const size_t kstep = (size_t)(BK * 2);
;     const size_t hstep = (size_t)HALF * K * 2;
;     const size_t tstep = 2 * hstep;
;     const unsigned ldsw = (unsigned)wid * 1024u;
;     const int aoff = lds_byte(wr * 64 + fr, fq * 8), boff = lds_byte(wc * 32 + fr, fq * 8);
;     ...
;     Unit cur, nxt; int ui = 0;
;     if (!S.next(0, cur)) return;
;     f32x4 acc[2][2][4][2];
; #pragma unroll
;     for (int a = 0; a < 2; ++a)
; #pragma unroll
;         for (int b = 0; b < 2; ++b)
; #pragma unroll
;             for (int m = 0; m < 4; ++m)
; #pragma unroll
;                 for (int n = 0; n < 2; ++n) acc[a][b][m][n] = (f32x4){0.f, 0.f, 0.f, 0.f};
;     h16x8 At[4][2], B0[2][2], B1[2][2];
;     const char* cA = (const char*)g.A + (size_t)cur.pm * tstep + cur.half * halfb; const char* cB = (const char*)g.Bt + (size_t)cur.pn * tstep + cur.half * halfb;
;     PG8_STAGE(PG8_SB(0, 0), cB); PG8_STAGE(PG8_SB(0, 1), cB + hstep); PG8_STAGE(PG8_SA(0, 0), cA); PG8_STAGE(PG8_SA(0, 1), cA + hstep);
;     if (wr == 1) PG8_BAR;
;     PG8_WAIT_V(2); PG8_BAR;
;     PG8_STAGE(PG8_SB(1, 0), cB + kstep); PG8_STAGE(PG8_SA(1, 0), cA + kstep); PG8_STAGE(PG8_SB(1, 1), cB + hstep + kstep);
;     PG8_WAIT_V(6); PG8_BAR;
.LBB0_147:
	s_and_b32 s16, s10, 3
	s_lshl_b32 s13, s1, 13
	s_lshl_b32 s17, s16, 12
	s_add_u32 s53, s53, 0x1c200000
	s_mov_b64 s[10:11], 0x80
	s_addc_u32 s7, s7, 0
	s_add_i32 m0, s51, 0x18000
	v_lshl_add_u64 v[6:7], v[6:7], 0, s[10:11]
	s_waitcnt vmcnt(2)
	s_barrier
	global_load_lds_dwordx4 v[6:7], off
	v_lshl_add_u64 v[4:5], v[4:5], 0, s[10:11]
	s_add_i32 m0, s51, 0x1a000
	s_add_i32 s67, s51, 0x8000
	s_add_i32 s68, s51, 0xa000
	global_load_lds_dwordx4 v[4:5], off
	v_lshl_add_u64 v[2:3], v[2:3], 0, s[10:11]
	s_mov_b32 m0, s67
	s_add_u32 s14, s42, 0x80080
	global_load_lds_dwordx4 v[2:3], off
	v_lshl_add_u64 v[0:1], v[0:1], 0, s[10:11]
	s_mov_b32 m0, s68
	s_addc_u32 s15, s43, 0
	global_load_lds_dwordx4 v[0:1], off
	s_add_i32 m0, s51, 0x1c000
	v_lshl_add_u64 v[0:1], s[14:15], 0, v[162:163]
	global_load_lds_dwordx4 v[0:1], off
	v_lshl_add_u64 v[0:1], s[14:15], 0, v[160:161]
	s_add_i32 m0, s51, 0x1e000
	v_lshlrev_b32_e32 v4, 2, v11
	global_load_lds_dwordx4 v[0:1], off
	v_and_b32_e32 v0, 15, v11
	v_bfe_u32 v1, v11, 4, 2
	v_lshlrev_b32_e32 v3, 6, v0
	v_lshlrev_b32_e32 v0, 3, v0
	v_lshlrev_b32_e32 v2, 3, v1
	v_lshl_or_b32 v3, v1, 4, v3
	v_lshl_or_b32 v0, v1, 7, v0
	v_lshlrev_b32_e32 v1, 15, v12
	v_and_b32_e32 v1, 0xffff0000, v1
	v_lshl_or_b32 v183, s16, 5, v2
	v_lshl_add_u32 v1, v13, 12, v1
	v_and_b32_e32 v2, 1, v12
	v_and_b32_e32 v4, 32, v4
	s_cmpk_lt_u32 s12, 0x100
	v_lshl_or_b32 v1, v2, 6, v1
	v_bitop3_b32 v5, v3, s13, v4 bitop3:0xde
	s_cselect_b64 s[12:13], -1, 0
	s_add_u32 s14, s8, 0x4000
	v_lshl_add_u32 v166, v14, 1, v1
	v_mov_b32_e32 v166, v162
	v_lshlrev_b32_e32 v1, 15, v8
	s_sext_i32_i8 s27, s0
	s_addc_u32 s15, s9, 0
	s_lshl_b32 s0, s1, 11
	s_lshl_b32 s1, s16, 9
	v_and_b32_e32 v1, 0xffff0000, v1
	s_waitcnt vmcnt(6)
	s_or_b32 s0, s1, s0
	v_lshl_add_u32 v1, v9, 12, v1
	v_and_b32_e32 v2, 1, v8
	v_bitop3_b32 v182, v3, s17, v4 bitop3:0xde
	s_ashr_i32 s1, s0, 31
	v_lshl_or_b32 v1, v2, 6, v1
	s_add_i32 s74, 0, 0x10000
	s_add_i32 s75, 0, 0x14000
	s_mov_b32 s69, 0x18000
	s_mov_b32 s70, 0x1a000
	s_mov_b32 s71, 0x8000
	s_mov_b32 s72, 0xa000
	s_mov_b32 s73, 0x1c000
	v_mov_b32_e32 v167, v165
	v_lshl_add_u32 v168, v10, 1, v1
	v_mov_b32_e32 v168, v160
	v_mov_b32_e32 v169, v165
	v_mov_b64_e32 v[170:171], 0x400
	v_mov_b64_e32 v[172:173], 0x3ff
	v_add_u32_e32 v184, s74, v182
	v_add_u32_e32 v185, s75, v182
	v_add_u32_e32 v186, 0, v5
	v_mbcnt_lo_u32_b32 v239, -1, 0
	v_mbcnt_hi_u32_b32 v239, -1, v239
	s_lshr_b32 s92, s33, 6
	s_lshr_b32 s93, s92, 2
	s_lshl_b32 s93, s93, 13
	s_and_b32 s94, s92, 3
	s_lshl_b32 s94, s94, 12
	v_and_b32_e32 v236, 15, v239
	v_lshrrev_b32_e32 v237, 4, v239
	v_lshrrev_b32_e32 v238, 1, v236
	v_xor_b32_e32 v237, v237, v238
	v_lshlrev_b32_e32 v237, 4, v237
	v_lshl_add_u32 v236, v236, 7, v237
	v_add_u32_e32 v186, s93, v236
	v_xor_b32_e32 v232, 64, v186
	v_add_u32_e32 v182, s94, v236
	v_xor_b32_e32 v233, 64, v182
	v_add_u32_e32 v184, 0x10000, v182
	v_add_u32_e32 v234, 0x10000, v233
	v_add_u32_e32 v185, 0x14000, v182
	v_add_u32_e32 v235, 0x14000, v233
	s_mov_b32 s76, 0xc000
	v_mov_b32_e32 v187, 0x7f7f7f7f
	s_lshl_b64 s[16:17], s[0:1], 1
	v_lshlrev_b32_e32 v164, 1, v0
	s_barrier
	s_branch .LBB0_150

.LBB0_157:
	ds_read_b128 v[24:27], v184
	ds_read_b128 v[28:31], v234
	ds_read_b128 v[16:19], v184 offset:2048
	ds_read_b128 v[20:23], v234 offset:2048
	ds_read_b128 v[8:11], v185
	ds_read_b128 v[12:15], v235
	ds_read_b128 v[0:3], v185 offset:2048
	ds_read_b128 v[4:7], v235 offset:2048
	s_add_u32 s42, s28, 0xfff80080
	s_addc_u32 s43, s29, -1
	s_cmp_eq_u32 s81, 28
	s_cselect_b32 s45, s21, s43
	s_cselect_b32 s44, s77, s42
	s_cselect_b32 s43, s19, s80
	s_cselect_b32 s42, s78, s79
	v_lshl_add_u64 v[214:215], s[28:29], 0, v[166:167]
	s_add_i32 m0, s51, 0xc000
	ds_read_b128 v[174:177], v186
	ds_read_b128 v[178:181], v232
	ds_read_b128 v[188:191], v186 offset:2048
	ds_read_b128 v[192:195], v232 offset:2048
	ds_read_b128 v[196:199], v186 offset:4096
	ds_read_b128 v[200:203], v232 offset:4096
	ds_read_b128 v[204:207], v186 offset:6144
	ds_read_b128 v[208:211], v232 offset:6144
	global_load_lds_dwordx4 v[214:215], off
	v_lshl_add_u64 v[214:215], s[28:29], 0, v[168:169]
	s_add_i32 m0, s51, 0xe000
	s_nop 0
	global_load_lds_dwordx4 v[214:215], off
	s_waitcnt vmcnt(8)
	s_waitcnt lgkmcnt(0)
	s_barrier
	s_setprio 1
	s_waitcnt lgkmcnt(0)
	v_mfma_scale_f32_16x16x128_f8f6f4 v[156:159], v[24:31], v[174:181], v[156:159], v187, v187 op_sel_hi:[0,0,0]
	v_mfma_scale_f32_16x16x128_f8f6f4 v[152:155], v[16:23], v[174:181], v[152:155], v187, v187 op_sel_hi:[0,0,0]
	v_mfma_scale_f32_16x16x128_f8f6f4 v[140:143], v[24:31], v[188:195], v[140:143], v187, v187 op_sel_hi:[0,0,0]
	v_mfma_scale_f32_16x16x128_f8f6f4 v[136:139], v[16:23], v[188:195], v[136:139], v187, v187 op_sel_hi:[0,0,0]
	v_mfma_scale_f32_16x16x128_f8f6f4 v[124:127], v[24:31], v[196:203], v[124:127], v187, v187 op_sel_hi:[0,0,0]
	v_mfma_scale_f32_16x16x128_f8f6f4 v[120:123], v[16:23], v[196:203], v[120:123], v187, v187 op_sel_hi:[0,0,0]
	v_mfma_scale_f32_16x16x128_f8f6f4 v[108:111], v[24:31], v[204:211], v[108:111], v187, v187 op_sel_hi:[0,0,0]
	v_mfma_scale_f32_16x16x128_f8f6f4 v[104:107], v[16:23], v[204:211], v[104:107], v187, v187 op_sel_hi:[0,0,0]
	s_setprio 0
	s_setprio 1
	v_mfma_scale_f32_16x16x128_f8f6f4 v[148:151], v[8:15], v[174:181], v[148:151], v187, v187 op_sel_hi:[0,0,0]
	v_mfma_scale_f32_16x16x128_f8f6f4 v[144:147], v[0:7], v[174:181], v[144:147], v187, v187 op_sel_hi:[0,0,0]
	v_mfma_scale_f32_16x16x128_f8f6f4 v[132:135], v[8:15], v[188:195], v[132:135], v187, v187 op_sel_hi:[0,0,0]
	v_mfma_scale_f32_16x16x128_f8f6f4 v[128:131], v[0:7], v[188:195], v[128:131], v187, v187 op_sel_hi:[0,0,0]
	v_mfma_scale_f32_16x16x128_f8f6f4 v[116:119], v[8:15], v[196:203], v[116:119], v187, v187 op_sel_hi:[0,0,0]
	v_mfma_scale_f32_16x16x128_f8f6f4 v[112:115], v[0:7], v[196:203], v[112:115], v187, v187 op_sel_hi:[0,0,0]
	v_mfma_scale_f32_16x16x128_f8f6f4 v[100:103], v[8:15], v[204:211], v[100:103], v187, v187 op_sel_hi:[0,0,0]
	v_mfma_scale_f32_16x16x128_f8f6f4 v[96:99], v[0:7], v[204:211], v[96:99], v187, v187 op_sel_hi:[0,0,0]
	s_setprio 0
	s_barrier
	s_add_i32 s82, s74, s46
	v_lshl_add_u64 v[174:175], s[42:43], 0, v[162:163]
	s_mov_b32 m0, s82
	ds_read_b128 v[188:191], v186 offset:16384
	ds_read_b128 v[192:195], v232 offset:16384
	ds_read_b128 v[196:199], v186 offset:18432
	ds_read_b128 v[200:203], v232 offset:18432
	ds_read_b128 v[204:207], v186 offset:20480
	ds_read_b128 v[208:211], v232 offset:20480
	ds_read_b128 v[214:217], v186 offset:22528
	ds_read_b128 v[218:221], v232 offset:22528
	global_load_lds_dwordx4 v[174:175], off
	s_add_i32 m0, s82, 0x2000
	s_add_u32 s82, s42, 0x80000
	v_lshl_add_u64 v[176:177], s[42:43], 0, v[160:161]
	s_addc_u32 s83, s43, 0
	s_add_i32 s84, s75, s46
	global_load_lds_dwordx4 v[176:177], off
	v_lshl_add_u64 v[178:179], s[82:83], 0, v[162:163]
	s_mov_b32 m0, s84
	v_lshl_add_u64 v[180:181], s[44:45], 0, v[160:161]
	global_load_lds_dwordx4 v[178:179], off
	v_lshl_add_u64 v[178:179], s[82:83], 0, v[160:161]
	s_add_i32 m0, s84, 0x2000
	s_nop 0
	global_load_lds_dwordx4 v[178:179], off
	v_lshl_add_u64 v[178:179], s[44:45], 0, v[162:163]
	s_mov_b32 m0, s51
	s_nop 0
	global_load_lds_dwordx4 v[178:179], off
	s_mov_b32 m0, s54
	s_nop 0
	global_load_lds_dwordx4 v[180:181], off
	s_waitcnt vmcnt(8)
	s_waitcnt lgkmcnt(0)
	s_barrier
	s_setprio 1
	s_waitcnt lgkmcnt(0)
	v_mfma_scale_f32_16x16x128_f8f6f4 v[92:95], v[24:31], v[188:195], v[92:95], v187, v187 op_sel_hi:[0,0,0]
	v_mfma_scale_f32_16x16x128_f8f6f4 v[88:91], v[16:23], v[188:195], v[88:91], v187, v187 op_sel_hi:[0,0,0]
	v_mfma_scale_f32_16x16x128_f8f6f4 v[76:79], v[24:31], v[196:203], v[76:79], v187, v187 op_sel_hi:[0,0,0]
	v_mfma_scale_f32_16x16x128_f8f6f4 v[72:75], v[16:23], v[196:203], v[72:75], v187, v187 op_sel_hi:[0,0,0]
	v_mfma_scale_f32_16x16x128_f8f6f4 v[60:63], v[24:31], v[204:211], v[60:63], v187, v187 op_sel_hi:[0,0,0]
	v_mfma_scale_f32_16x16x128_f8f6f4 v[56:59], v[16:23], v[204:211], v[56:59], v187, v187 op_sel_hi:[0,0,0]
	v_mfma_scale_f32_16x16x128_f8f6f4 v[44:47], v[24:31], v[214:221], v[44:47], v187, v187 op_sel_hi:[0,0,0]
	v_mfma_scale_f32_16x16x128_f8f6f4 v[40:43], v[16:23], v[214:221], v[40:43], v187, v187 op_sel_hi:[0,0,0]
	s_setprio 0
	s_setprio 1
	v_mfma_scale_f32_16x16x128_f8f6f4 v[84:87], v[8:15], v[188:195], v[84:87], v187, v187 op_sel_hi:[0,0,0]
	v_mfma_scale_f32_16x16x128_f8f6f4 v[80:83], v[0:7], v[188:195], v[80:83], v187, v187 op_sel_hi:[0,0,0]
	v_mfma_scale_f32_16x16x128_f8f6f4 v[68:71], v[8:15], v[196:203], v[68:71], v187, v187 op_sel_hi:[0,0,0]
	v_mfma_scale_f32_16x16x128_f8f6f4 v[64:67], v[0:7], v[196:203], v[64:67], v187, v187 op_sel_hi:[0,0,0]
	v_mfma_scale_f32_16x16x128_f8f6f4 v[52:55], v[8:15], v[204:211], v[52:55], v187, v187 op_sel_hi:[0,0,0]
	v_mfma_scale_f32_16x16x128_f8f6f4 v[48:51], v[0:7], v[204:211], v[48:51], v187, v187 op_sel_hi:[0,0,0]
	v_mfma_scale_f32_16x16x128_f8f6f4 v[36:39], v[8:15], v[214:221], v[36:39], v187, v187 op_sel_hi:[0,0,0]
	v_mfma_scale_f32_16x16x128_f8f6f4 v[32:35], v[0:7], v[214:221], v[32:35], v187, v187 op_sel_hi:[0,0,0]
	s_setprio 0
	s_barrier
; template <class Epi, class Sched, bool FP8 = false>
; __device__ __forceinline__ void gemm_phase(LAS unsigned char* lds, const Gemm g, const Sched& S, const Epi& E, const int tid) {
;     ...
;         for (int t = 0; t < nt; t += 2) PG8_KBODY(t);
	s_add_i32 s82, 0, 0x18000
	s_add_i32 s83, 0, 0x1c000
	v_add_u32_e32 v12, s82, v182
	v_add_u32_e32 v230, s82, v233
	v_add_u32_e32 v28, s83, v182
	v_add_u32_e32 v231, s83, v233
	ds_read_b128 v[0:3], v12
	ds_read_b128 v[4:7], v230
	ds_read_b128 v[8:11], v12 offset:2048
	ds_read_b128 v[12:15], v230 offset:2048
	ds_read_b128 v[16:19], v28
	ds_read_b128 v[20:23], v231
	ds_read_b128 v[24:27], v28 offset:2048
	ds_read_b128 v[28:31], v231 offset:2048
	s_add_u32 s44, s44, 0x80000
	s_addc_u32 s45, s45, 0
	s_mov_b32 m0, s55
	v_lshl_add_u64 v[222:223], s[44:45], 0, v[162:163]
	ds_read_b128 v[188:191], v186 offset:32768
	ds_read_b128 v[192:195], v232 offset:32768
	ds_read_b128 v[196:199], v186 offset:34816
	ds_read_b128 v[200:203], v232 offset:34816
	ds_read_b128 v[204:207], v186 offset:36864
	ds_read_b128 v[208:211], v232 offset:36864
	ds_read_b128 v[214:217], v186 offset:38912
	ds_read_b128 v[218:221], v232 offset:38912
	global_load_lds_dwordx4 v[222:223], off
	v_lshl_add_u64 v[222:223], s[44:45], 0, v[160:161]
	s_mov_b32 m0, s56
	s_nop 0
	global_load_lds_dwordx4 v[222:223], off
	s_waitcnt vmcnt(8)
	s_waitcnt lgkmcnt(0)
	s_barrier
	s_setprio 1
	s_waitcnt lgkmcnt(0)
	v_mfma_scale_f32_16x16x128_f8f6f4 v[156:159], v[0:7], v[188:195], v[156:159], v187, v187 op_sel_hi:[0,0,0]
	v_mfma_scale_f32_16x16x128_f8f6f4 v[152:155], v[8:15], v[188:195], v[152:155], v187, v187 op_sel_hi:[0,0,0]
	v_mfma_scale_f32_16x16x128_f8f6f4 v[140:143], v[0:7], v[196:203], v[140:143], v187, v187 op_sel_hi:[0,0,0]
	v_mfma_scale_f32_16x16x128_f8f6f4 v[136:139], v[8:15], v[196:203], v[136:139], v187, v187 op_sel_hi:[0,0,0]
	v_mfma_scale_f32_16x16x128_f8f6f4 v[124:127], v[0:7], v[204:211], v[124:127], v187, v187 op_sel_hi:[0,0,0]
	v_mfma_scale_f32_16x16x128_f8f6f4 v[120:123], v[8:15], v[204:211], v[120:123], v187, v187 op_sel_hi:[0,0,0]
	v_mfma_scale_f32_16x16x128_f8f6f4 v[108:111], v[0:7], v[214:221], v[108:111], v187, v187 op_sel_hi:[0,0,0]
	v_mfma_scale_f32_16x16x128_f8f6f4 v[104:107], v[8:15], v[214:221], v[104:107], v187, v187 op_sel_hi:[0,0,0]
	s_setprio 0
	s_setprio 1
	v_mfma_scale_f32_16x16x128_f8f6f4 v[148:151], v[16:23], v[188:195], v[148:151], v187, v187 op_sel_hi:[0,0,0]
	v_mfma_scale_f32_16x16x128_f8f6f4 v[144:147], v[24:31], v[188:195], v[144:147], v187, v187 op_sel_hi:[0,0,0]
	v_mfma_scale_f32_16x16x128_f8f6f4 v[132:135], v[16:23], v[196:203], v[132:135], v187, v187 op_sel_hi:[0,0,0]
	v_mfma_scale_f32_16x16x128_f8f6f4 v[128:131], v[24:31], v[196:203], v[128:131], v187, v187 op_sel_hi:[0,0,0]
	v_mfma_scale_f32_16x16x128_f8f6f4 v[116:119], v[16:23], v[204:211], v[116:119], v187, v187 op_sel_hi:[0,0,0]
	v_mfma_scale_f32_16x16x128_f8f6f4 v[112:115], v[24:31], v[204:211], v[112:115], v187, v187 op_sel_hi:[0,0,0]
	v_mfma_scale_f32_16x16x128_f8f6f4 v[100:103], v[16:23], v[214:221], v[100:103], v187, v187 op_sel_hi:[0,0,0]
	v_mfma_scale_f32_16x16x128_f8f6f4 v[96:99], v[24:31], v[214:221], v[96:99], v187, v187 op_sel_hi:[0,0,0]
	s_setprio 0
	s_barrier
	s_add_i32 s44, s82, s46
	v_lshl_add_u64 v[174:175], v[174:175], 0, s[10:11]
	s_mov_b32 m0, s44
	ds_read_b128 v[188:191], v186 offset:49152
	ds_read_b128 v[192:195], v232 offset:49152
	ds_read_b128 v[196:199], v186 offset:51200
	ds_read_b128 v[200:203], v232 offset:51200
	ds_read_b128 v[204:207], v186 offset:53248
	ds_read_b128 v[208:211], v232 offset:53248
	ds_read_b128 v[214:217], v186 offset:55296
	ds_read_b128 v[218:221], v232 offset:55296
	global_load_lds_dwordx4 v[174:175], off
	s_add_i32 m0, s44, 0x2000
	s_add_u32 s42, s42, 0x80080
	v_lshl_add_u64 v[174:175], v[176:177], 0, s[10:11]
	s_addc_u32 s43, s43, 0
	s_add_i32 s44, s83, s46
	global_load_lds_dwordx4 v[174:175], off
	v_lshl_add_u64 v[174:175], s[42:43], 0, v[162:163]
	s_mov_b32 m0, s44
	s_nop 0
	global_load_lds_dwordx4 v[174:175], off
	v_lshl_add_u64 v[174:175], s[42:43], 0, v[160:161]
	s_add_i32 m0, s44, 0x2000
	s_nop 0
	global_load_lds_dwordx4 v[174:175], off
	v_lshl_add_u64 v[174:175], v[178:179], 0, s[10:11]
	s_mov_b32 m0, s67
	s_nop 0
	global_load_lds_dwordx4 v[174:175], off
	v_lshl_add_u64 v[174:175], v[180:181], 0, s[10:11]
	s_mov_b32 m0, s68
	s_nop 0
	global_load_lds_dwordx4 v[174:175], off
	s_waitcnt vmcnt(8)
	s_waitcnt lgkmcnt(0)
	s_barrier
	s_setprio 1
	s_waitcnt lgkmcnt(0)
	v_mfma_scale_f32_16x16x128_f8f6f4 v[92:95], v[0:7], v[188:195], v[92:95], v187, v187 op_sel_hi:[0,0,0]
	v_mfma_scale_f32_16x16x128_f8f6f4 v[88:91], v[8:15], v[188:195], v[88:91], v187, v187 op_sel_hi:[0,0,0]
	v_mfma_scale_f32_16x16x128_f8f6f4 v[76:79], v[0:7], v[196:203], v[76:79], v187, v187 op_sel_hi:[0,0,0]
	v_mfma_scale_f32_16x16x128_f8f6f4 v[72:75], v[8:15], v[196:203], v[72:75], v187, v187 op_sel_hi:[0,0,0]
	v_mfma_scale_f32_16x16x128_f8f6f4 v[60:63], v[0:7], v[204:211], v[60:63], v187, v187 op_sel_hi:[0,0,0]
	v_mfma_scale_f32_16x16x128_f8f6f4 v[56:59], v[8:15], v[204:211], v[56:59], v187, v187 op_sel_hi:[0,0,0]
	v_mfma_scale_f32_16x16x128_f8f6f4 v[44:47], v[0:7], v[214:221], v[44:47], v187, v187 op_sel_hi:[0,0,0]
	v_mfma_scale_f32_16x16x128_f8f6f4 v[40:43], v[8:15], v[214:221], v[40:43], v187, v187 op_sel_hi:[0,0,0]
	s_setprio 0
	s_setprio 1
	v_mfma_scale_f32_16x16x128_f8f6f4 v[84:87], v[16:23], v[188:195], v[84:87], v187, v187 op_sel_hi:[0,0,0]
	v_mfma_scale_f32_16x16x128_f8f6f4 v[80:83], v[24:31], v[188:195], v[80:83], v187, v187 op_sel_hi:[0,0,0]
	v_mfma_scale_f32_16x16x128_f8f6f4 v[68:71], v[16:23], v[196:203], v[68:71], v187, v187 op_sel_hi:[0,0,0]
	v_mfma_scale_f32_16x16x128_f8f6f4 v[64:67], v[24:31], v[196:203], v[64:67], v187, v187 op_sel_hi:[0,0,0]
	v_mfma_scale_f32_16x16x128_f8f6f4 v[52:55], v[16:23], v[204:211], v[52:55], v187, v187 op_sel_hi:[0,0,0]
	v_mfma_scale_f32_16x16x128_f8f6f4 v[48:51], v[24:31], v[204:211], v[48:51], v187, v187 op_sel_hi:[0,0,0]
	v_mfma_scale_f32_16x16x128_f8f6f4 v[36:39], v[16:23], v[214:221], v[36:39], v187, v187 op_sel_hi:[0,0,0]
	v_mfma_scale_f32_16x16x128_f8f6f4 v[32:35], v[24:31], v[214:221], v[32:35], v187, v187 op_sel_hi:[0,0,0]
	s_setprio 0
	s_barrier
	s_add_i32 s81, s81, 2
	s_add_u32 s28, s28, 0x100
	s_addc_u32 s29, s29, 0
	s_add_u32 s79, s79, 0x100
	s_addc_u32 s80, s80, 0
	s_cmp_gt_u32 s81, 29
	s_cbranch_scc0 .LBB0_157
	s_and_b64 vcc, exec, s[12:13]
	s_cbranch_vccz .LBB0_160
	s_barrier

; #define REP(k) for (int rep_ = 0; rep_ < (((REPMASK >> (k)) & 1) ? 2 : 1); ++rep_)
; template <class Epi, class Sched, bool FP8 = false>
; __device__ __forceinline__ void gemm_phase(LAS unsigned char* lds, const Gemm g, const Sched& S, const Epi& E, const int tid) {
;     const int wid = __builtin_amdgcn_readfirstlane(tid >> 6), lane = tid & 63, wr = wid >> 2, wc = wid & 3, fr = lane & 15, fq = lane >> 4;
;     const int K = g.K, nt = g.Kloop / BK;
;     const size_t halfb = (size_t)g.Kloop * 2;
;     const int sc8 = 0x7f7f7f7f;
;     unsigned voffA[2];
; #pragma unroll
;     for (int i = 0; i < 2; ++i) { int R, C; stage_rc(tid * 16 + i * 8192, R, C); voffA[i] = (unsigned)(R * K + C) * 2u; }
;     const size_t kstep = (size_t)(BK * 2);
;     const size_t hstep = (size_t)HALF * K * 2;
;     const size_t tstep = 2 * hstep;
;     const unsigned ldsw = (unsigned)wid * 1024u;
;     const int aoff = lds_byte(wr * 64 + fr, fq * 8), boff = lds_byte(wc * 32 + fr, fq * 8);
;     ...
;     Unit cur, nxt; int ui = 0;
;     if (!S.next(0, cur)) return;
;     f32x4 acc[2][2][4][2];
; #pragma unroll
;     for (int a = 0; a < 2; ++a)
; #pragma unroll
;         for (int b = 0; b < 2; ++b)
; #pragma unroll
;             for (int m = 0; m < 4; ++m)
; #pragma unroll
;                 for (int n = 0; n < 2; ++n) acc[a][b][m][n] = (f32x4){0.f, 0.f, 0.f, 0.f};
;     h16x8 At[4][2], B0[2][2], B1[2][2];
;     const char* cA = (const char*)g.A + (size_t)cur.pm * tstep + cur.half * halfb; const char* cB = (const char*)g.Bt + (size_t)cur.pn * tstep + cur.half * halfb;
;     PG8_STAGE(PG8_SB(0, 0), cB); PG8_STAGE(PG8_SB(0, 1), cB + hstep); PG8_STAGE(PG8_SA(0, 0), cA); PG8_STAGE(PG8_SA(0, 1), cA + hstep);
;     if (wr == 1) PG8_BAR;
;     PG8_WAIT_V(2); PG8_BAR;
;     PG8_STAGE(PG8_SB(1, 0), cB + kstep); PG8_STAGE(PG8_SA(1, 0), cA + kstep); PG8_STAGE(PG8_SB(1, 1), cB + hstep + kstep);
;     PG8_WAIT_V(6); PG8_BAR;
; template <int COOP>
; __global__ void __launch_bounds__(512, 2) mega(Args a) {
;     ...
;     if (IN(4)) REP(4) { const Ptrs P = mkptrs(ptab);
;         h3_phase(P, lds, bx, G, fresh_tid());
;         __syncthreads();
;     }
;     SEAM(4);
;     if (IN(5)) REP(5) { const Ptrs P = mkptrs(ptab);
;         pg8::Gemm g{P.YAB, P.WABT, T, D, 4096, HW}; pg8::StaticOrder S; S.init(T, D, G, bx, 2, 4);
;         pg8::EpiG2 E{P.PG, P.MG};
;         pg8::gemm_phase(lds, g, S, E, fresh_tid());
.LBB0_458:
	s_or_b64 exec, exec, s[0:1]
	s_cmpk_lt_i32 s2, 0x200
	s_cselect_b64 s[6:7], -1, 0
	s_add_i32 s0, 0, 0x24060
	s_waitcnt lgkmcnt(0)
	v_mov_b32_e32 v0, s0
	s_barrier
	ds_read_b64 v[0:1], v0
	v_mbcnt_lo_u32_b32 v12, -1, 0
	v_mbcnt_hi_u32_b32 v12, -1, v12
	s_and_b64 vcc, exec, s[6:7]
	s_waitcnt lgkmcnt(0)
	v_readfirstlane_b32 s12, v0
	v_or_b32_e32 v0, s33, v12
	v_readfirstlane_b32 s13, v1
	v_readfirstlane_b32 s1, v0
	s_cbranch_vccz .LBB0_488
	v_lshlrev_b32_e32 v1, 4, v0
	v_add_u32_e32 v2, 0x2000, v1
	v_ashrrev_i32_e32 v3, 31, v2
	v_lshrrev_b32_e32 v3, 22, v3
	v_add_u32_e32 v3, v2, v3
	v_ashrrev_i32_e32 v8, 10, v3
	v_mul_i32_i24_e32 v4, 0x400, v8
	v_sub_u32_e32 v2, v2, v4
	v_lshrrev_b32_e32 v4, 4, v2
	v_bitop3_b32 v2, v4, v2, 32 bitop3:0x6c
	v_ashrrev_i32_e32 v4, 31, v2
	v_lshrrev_b32_e32 v4, 26, v4
	v_add_u32_e32 v4, v2, v4
	s_add_u32 s50, s12, 0xc200000
	v_ashrrev_i32_e32 v9, 6, v4
	v_and_b32_e32 v4, 0xc0, v4
	s_addc_u32 s51, s13, 0
	v_sub_u32_e32 v2, v2, v4
	v_mov_b32_e32 v4, 1
	s_add_u32 s52, s12, 0x28200000
	v_lshlrev_b32_e32 v3, 5, v8
	v_ashrrev_i16_sdwa v2, v4, sext(v2) dst_sel:DWORD dst_unused:UNUSED_PAD src0_sel:DWORD src1_sel:BYTE_0
	s_addc_u32 s53, s13, 0
	s_ashr_i32 s14, s1, 6
	v_and_b32_e32 v3, 32, v3
	v_bfe_i32 v10, v2, 0, 16
	s_ashr_i32 s18, s1, 8
	s_lshl_b32 s54, s14, 10
	v_add_u32_e32 v2, v3, v10
	v_lshlrev_b32_e32 v3, 3, v8
	s_lshl_b32 s8, s65, 6
	v_and_b32_e32 v3, 0x7fff0, v3
	s_mul_i32 s0, s65, 0x41
	s_and_b64 s[4:5], s[40:41], exec
	v_add_lshl_u32 v3, v9, v3, 13
	s_cselect_b32 s0, s0, s8
	v_lshl_add_u32 v128, v2, 1, v3
	v_ashrrev_i32_e32 v2, 31, v0
	s_add_i32 s0, s0, s64
	v_lshrrev_b32_e32 v2, 26, v2
	s_ashr_i32 s4, s0, 31
	v_add_u32_e32 v2, v0, v2
	v_bfe_i32 v0, v0, 27, 1
	s_lshr_b32 s4, s4, 26
	v_lshrrev_b32_e32 v0, 22, v0
	s_add_i32 s4, s0, s4
	v_add_u32_e32 v0, v1, v0
	s_ashr_i32 s5, s4, 6
	s_and_b32 s4, s4, 0xffc0
	v_and_b32_e32 v0, 0xfffffc00, v0
	s_sub_i32 s4, s0, s4
	v_sub_u32_e32 v0, v1, v0
	s_bfe_i32 s0, s4, 0x80000
	v_lshrrev_b32_e32 v1, 4, v0
	s_bfe_u32 s0, s0, 0x2000d
	v_bitop3_b32 v0, v1, v0, 32 bitop3:0x6c
	s_add_i32 s8, s4, s0
	v_ashrrev_i32_e32 v1, 31, v0
	s_bfe_i32 s0, s8, 0x80000
	s_and_b32 s8, s8, 0xfc
	v_lshrrev_b32_e32 v1, 26, v1
	s_sub_i32 s4, s4, s8
	v_add_u32_e32 v1, v0, v1
	s_lshl_b32 s5, s5, 2
	s_sext_i32_i16 s0, s0
	s_sext_i32_i8 s4, s4
	v_ashrrev_i32_e32 v13, 6, v1
	v_and_b32_e32 v1, 0xc0, v1
	s_lshr_b32 s0, s0, 2
	s_add_i32 s44, s5, s4
	v_ashrrev_i32_e32 v11, 6, v2
	v_sub_u32_e32 v0, v0, v1
	s_ashr_i32 s45, s44, 31
	s_bfe_i64 s[8:9], s[0:1], 0x100000
	v_lshlrev_b32_e32 v2, 5, v11
	v_ashrrev_i16_sdwa v0, v4, sext(v0) dst_sel:DWORD dst_unused:UNUSED_PAD src0_sel:DWORD src1_sel:BYTE_0
	v_lshlrev_b32_e32 v1, 3, v11
	s_lshl_b64 s[4:5], s[44:45], 21
	s_lshl_b64 s[8:9], s[8:9], 21
	v_and_b32_e32 v2, 32, v2
	v_bfe_i32 v14, v0, 0, 16
	v_and_b32_e32 v1, 0x7fff0, v1
	s_add_u32 s46, s50, s8
	v_add_u32_e32 v0, v2, v14
	v_add_lshl_u32 v1, v13, v1, 13
	s_addc_u32 s47, s51, s9
	s_add_i32 s55, s54, 0
	v_lshl_add_u32 v130, v0, 1, v1
	v_mbcnt_lo_u32_b32 v239, -1, 0
	v_mbcnt_hi_u32_b32 v239, -1, v239
	s_lshr_b32 s92, s33, 6
	s_lshl_b32 s93, s92, 3
	s_and_b32 s94, s92, 1
	s_lshl_b32 s94, s94, 2
	v_lshrrev_b32_e32 v236, 3, v239
	v_add_u32_e32 v236, s93, v236
	v_lshrrev_b32_e32 v237, 4, v239
	v_add_u32_e32 v237, s94, v237
	v_and_b32_e32 v238, 7, v239
	v_xor_b32_e32 v237, v238, v237
	v_lshlrev_b32_e32 v237, 4, v237
	v_lshl_add_u32 v130, v236, 13, v237
	v_add_u32_e32 v128, 0x80000, v130
	s_add_i32 m0, s55, 0x10000
	v_mov_b32_e32 v133, 0
	global_load_lds_dwordx4 v130, s[46:47]
	s_add_i32 m0, s55, 0x12000
	s_add_u32 s8, s46, 0x100000
	global_load_lds_dwordx4 v128, s[46:47]
	s_addc_u32 s9, s47, 0
	s_add_i32 m0, s55, 0x14000
	v_mov_b32_e32 v131, v133
	global_load_lds_dwordx4 v130, s[8:9]
	s_add_i32 m0, s55, 0x16000
	s_add_u32 s4, s52, s4
	s_addc_u32 s5, s53, s5
	s_add_i32 s56, s55, 0x2000
	global_load_lds_dwordx4 v128, s[8:9]
	s_mov_b32 m0, s55
	s_add_u32 s8, s4, 0x100000
	global_load_lds_dwordx4 v130, s[4:5]
	s_mov_b32 m0, s56
	s_addc_u32 s9, s5, 0
	s_add_i32 s57, s55, 0x4000
	global_load_lds_dwordx4 v128, s[4:5]
	s_mov_b32 m0, s57
	s_add_i32 s58, s55, 0x6000
	global_load_lds_dwordx4 v130, s[8:9]
	s_mov_b32 m0, s58
	v_mov_b32_e32 v129, v133
	global_load_lds_dwordx4 v128, s[8:9]
	s_cmp_eq_u32 s18, 1
	s_movk_i32 s59, 0x2000
	v_lshl_add_u64 v[6:7], s[46:47], 0, v[130:131]
	v_lshl_add_u64 v[4:5], s[46:47], 0, v[128:129]
	s_mov_b64 s[8:9], 0x100000
	v_lshl_add_u64 v[2:3], s[4:5], 0, v[130:131]
	v_lshl_add_u64 v[0:1], s[4:5], 0, v[128:129]
	s_cselect_b64 s[10:11], -1, 0
	s_cmp_lg_u32 s18, 1
	s_movk_i32 s60, 0x4000
	s_cbranch_scc1 .LBB0_461
	s_barrier
; #define PG8_STAGE(bufoff, gbase) do { _Pragma("unroll") for (int _i = 0; _i < 2; ++_i) \
;         __builtin_amdgcn_global_load_lds((const unsigned*)((const char*)(gbase) + voffA[_i]), (LAS unsigned*)(lds + (bufoff) + ldsw + _i * 8192), 16, 0, 0); } while (0)
; #define PG8_WAIT_V(n) asm volatile("s_waitcnt vmcnt(" #n ")" ::: "memory")
; #define PG8_BAR __builtin_amdgcn_s_barrier()
; template <class Epi, class Sched, bool FP8 = false>
; __device__ __forceinline__ void gemm_phase(LAS unsigned char* lds, const Gemm g, const Sched& S, const Epi& E, const int tid) {
;     const int wid = __builtin_amdgcn_readfirstlane(tid >> 6), lane = tid & 63, wr = wid >> 2, wc = wid & 3, fr = lane & 15, fq = lane >> 4;
;     const int K = g.K, nt = g.Kloop / BK;
;     const size_t halfb = (size_t)g.Kloop * 2;
;     const int sc8 = 0x7f7f7f7f;
;     unsigned voffA[2];
; #pragma unroll
;     for (int i = 0; i < 2; ++i) { int R, C; stage_rc(tid * 16 + i * 8192, R, C); voffA[i] = (unsigned)(R * K + C) * 2u; }
;     const size_t kstep = (size_t)(BK * 2);
;     const size_t hstep = (size_t)HALF * K * 2;
;     const size_t tstep = 2 * hstep;
;     const unsigned ldsw = (unsigned)wid * 1024u;
;     const int aoff = lds_byte(wr * 64 + fr, fq * 8), boff = lds_byte(wc * 32 + fr, fq * 8);
;     ...
;     Unit cur, nxt; int ui = 0;
;     if (!S.next(0, cur)) return;
;     f32x4 acc[2][2][4][2];
; #pragma unroll
;     for (int a = 0; a < 2; ++a)
; #pragma unroll
;         for (int b = 0; b < 2; ++b)
; #pragma unroll
;             for (int m = 0; m < 4; ++m)
; #pragma unroll
;                 for (int n = 0; n < 2; ++n) acc[a][b][m][n] = (f32x4){0.f, 0.f, 0.f, 0.f};
;     h16x8 At[4][2], B0[2][2], B1[2][2];
;     const char* cA = (const char*)g.A + (size_t)cur.pm * tstep + cur.half * halfb; const char* cB = (const char*)g.Bt + (size_t)cur.pn * tstep + cur.half * halfb;
;     PG8_STAGE(PG8_SB(0, 0), cB); PG8_STAGE(PG8_SB(0, 1), cB + hstep); PG8_STAGE(PG8_SA(0, 0), cA); PG8_STAGE(PG8_SA(0, 1), cA + hstep);
;     if (wr == 1) PG8_BAR;
;     PG8_WAIT_V(2); PG8_BAR;
;     PG8_STAGE(PG8_SB(1, 0), cB + kstep); PG8_STAGE(PG8_SA(1, 0), cA + kstep); PG8_STAGE(PG8_SB(1, 1), cB + hstep + kstep);
;     PG8_WAIT_V(6); PG8_BAR;
.LBB0_461:
	s_add_u32 s61, s12, 0x1c200000
	s_addc_u32 s62, s13, 0
	v_bfe_u32 v16, v12, 4, 2
	s_add_u32 s12, s12, 0x34200000
	v_and_b32_e32 v15, 15, v12
	v_lshlrev_b32_e32 v18, 4, v16
	v_lshlrev_b32_e32 v12, 2, v12
	s_sext_i32_i8 s45, s0
	s_addc_u32 s13, s13, 0
	s_and_b32 s0, s14, 3
	v_lshl_or_b32 v18, v15, 6, v18
	s_lshl_b32 s14, s18, 13
	v_and_b32_e32 v12, 32, v12
	v_bitop3_b32 v19, v18, s14, v12 bitop3:0xde
	s_lshl_b32 s14, s0, 12
	v_bitop3_b32 v214, v18, s14, v12 bitop3:0xde
	s_mov_b64 s[14:15], 0x80
	s_add_i32 m0, s55, 0x18000
	v_lshl_add_u64 v[6:7], v[6:7], 0, s[14:15]
	s_waitcnt vmcnt(2)
	s_barrier
	global_load_lds_dwordx4 v[6:7], off
	v_lshl_add_u64 v[4:5], v[4:5], 0, s[14:15]
	s_add_i32 m0, s55, 0x1a000
	s_add_i32 s66, s55, 0x8000
	s_add_i32 s68, s55, 0xa000
	global_load_lds_dwordx4 v[4:5], off
	v_lshl_add_u64 v[2:3], v[2:3], 0, s[14:15]
	s_mov_b32 m0, s66
	s_add_u32 s16, s46, 0x100080
	global_load_lds_dwordx4 v[2:3], off
	v_lshl_add_u64 v[0:1], v[0:1], 0, s[14:15]
	s_mov_b32 m0, s68
	s_addc_u32 s17, s47, 0
	global_load_lds_dwordx4 v[0:1], off
	s_add_i32 m0, s55, 0x1c000
	v_lshl_add_u64 v[0:1], s[16:17], 0, v[130:131]
	global_load_lds_dwordx4 v[0:1], off
	v_lshl_add_u64 v[0:1], s[16:17], 0, v[128:129]
	s_add_i32 m0, s55, 0x1e000
	v_lshlrev_b32_e32 v17, 3, v16
	global_load_lds_dwordx4 v[0:1], off
	v_lshlrev_b32_e32 v0, 3, v15
	v_lshl_or_b32 v4, v16, 7, v0
	v_lshlrev_b32_e32 v0, 16, v11
	v_and_b32_e32 v0, 0xfffe0000, v0
	v_lshl_add_u32 v0, v13, 13, v0
	v_and_b32_e32 v1, 1, v11
	v_lshl_or_b32 v0, v1, 6, v0
	v_lshl_add_u32 v134, v14, 1, v0
	v_mov_b32_e32 v134, v130
	v_lshlrev_b32_e32 v0, 16, v8
	s_cmpk_lt_u32 s1, 0x100
	v_and_b32_e32 v0, 0xfffe0000, v0
	v_lshl_or_b32 v215, s0, 5, v17
	s_cselect_b64 s[16:17], -1, 0
	s_lshl_b32 s1, s18, 11
	s_lshl_b32 s0, s0, 9
	v_lshl_add_u32 v0, v9, 13, v0
	v_and_b32_e32 v1, 1, v8
	s_waitcnt vmcnt(6)
	s_or_b32 s0, s0, s1
	v_lshl_or_b32 v0, v1, 6, v0
	v_mov_b32_e32 v2, v133
	v_mov_b32_e32 v3, v133
	v_lshl_or_b32 v213, s18, 6, v15
	s_ashr_i32 s1, s0, 31
	v_lshl_add_u32 v136, v10, 1, v0
	v_mov_b32_e32 v136, v128
	v_mov_b32_e32 v0, v133
	v_mov_b32_e32 v1, v133
	v_add_u32_e32 v216, 0, v19
	v_mbcnt_lo_u32_b32 v239, -1, 0
	v_mbcnt_hi_u32_b32 v239, -1, v239
	s_lshr_b32 s92, s33, 6
	s_lshr_b32 s93, s92, 2
	s_lshl_b32 s93, s93, 13
	s_and_b32 s94, s92, 3
	s_lshl_b32 s94, s94, 12
	v_and_b32_e32 v236, 15, v239
	v_lshrrev_b32_e32 v237, 4, v239
	v_lshrrev_b32_e32 v238, 1, v236
	v_xor_b32_e32 v237, v237, v238
	v_lshlrev_b32_e32 v237, 4, v237
	v_lshl_add_u32 v236, v236, 7, v237
	v_add_u32_e32 v216, s93, v236
	v_xor_b32_e32 v232, 64, v216
	v_add_u32_e32 v214, s94, v236
	v_xor_b32_e32 v233, 64, v214
	v_lshlrev_b32_e32 v132, 1, v4
	v_mov_b64_e32 v[6:7], v[2:3]
	v_mov_b64_e32 v[10:11], v[2:3]
	v_mov_b64_e32 v[14:15], v[2:3]
	v_mov_b64_e32 v[18:19], v[2:3]
	v_mov_b64_e32 v[22:23], v[2:3]
	v_mov_b64_e32 v[26:27], v[2:3]
	v_mov_b64_e32 v[30:31], v[2:3]
	v_mov_b64_e32 v[34:35], v[2:3]
	v_mov_b64_e32 v[38:39], v[2:3]
	v_mov_b64_e32 v[42:43], v[2:3]
	v_mov_b64_e32 v[46:47], v[2:3]
	v_mov_b64_e32 v[50:51], v[2:3]
	v_mov_b64_e32 v[54:55], v[2:3]
	v_mov_b64_e32 v[58:59], v[2:3]
	v_mov_b64_e32 v[62:63], v[2:3]
	v_mov_b64_e32 v[66:67], v[2:3]
	v_mov_b64_e32 v[70:71], v[2:3]
	v_mov_b64_e32 v[74:75], v[2:3]
	v_mov_b64_e32 v[78:79], v[2:3]
	v_mov_b64_e32 v[82:83], v[2:3]
	v_mov_b64_e32 v[86:87], v[2:3]
	v_mov_b64_e32 v[90:91], v[2:3]
	v_mov_b64_e32 v[94:95], v[2:3]
	v_mov_b64_e32 v[98:99], v[2:3]
	v_mov_b64_e32 v[102:103], v[2:3]
	v_mov_b64_e32 v[106:107], v[2:3]
	v_mov_b64_e32 v[110:111], v[2:3]
	v_mov_b64_e32 v[114:115], v[2:3]
	v_mov_b64_e32 v[118:119], v[2:3]
	v_mov_b64_e32 v[122:123], v[2:3]
	v_mov_b64_e32 v[126:127], v[2:3]
	s_mov_b32 s63, 0x8000
	s_mov_b32 s67, 0xa000
	v_mov_b32_e32 v135, v133
	v_mov_b32_e32 v137, v133
	s_mov_b32 s80, 0
	v_mov_b64_e32 v[138:139], 0x200
	v_mov_b64_e32 v[140:141], 0x1ff
	s_add_i32 s69, 0, 0x10000
	s_add_i32 s70, 0, 0x14000
	s_mov_b32 s71, 0xc000
	s_lshl_b64 s[18:19], s[0:1], 1
	s_mov_b32 s72, 0x20000
	s_mov_b32 s73, 0x28000
	s_mov_b32 s74, 0x100000
	s_mov_b64 s[20:21], 0x120000
	s_mov_b32 s75, 0x120000
	s_mov_b64 s[22:23], 0x140000
	s_mov_b32 s76, 0x140000
	s_mov_b64 s[24:25], 0x160000
	s_mov_b32 s77, 0x160000
	v_mov_b64_e32 v[4:5], v[0:1]
	v_mov_b64_e32 v[8:9], v[0:1]
	v_mov_b64_e32 v[12:13], v[0:1]
	v_mov_b64_e32 v[16:17], v[0:1]
	v_mov_b64_e32 v[20:21], v[0:1]
	v_mov_b64_e32 v[24:25], v[0:1]
	v_mov_b64_e32 v[28:29], v[0:1]
	v_mov_b64_e32 v[32:33], v[0:1]
	v_mov_b64_e32 v[36:37], v[0:1]
	v_mov_b64_e32 v[40:41], v[0:1]
	v_mov_b64_e32 v[44:45], v[0:1]
	v_mov_b64_e32 v[48:49], v[0:1]
	v_mov_b64_e32 v[52:53], v[0:1]
	v_mov_b64_e32 v[56:57], v[0:1]
	v_mov_b64_e32 v[60:61], v[0:1]
	v_mov_b64_e32 v[64:65], v[0:1]
	v_mov_b64_e32 v[68:69], v[0:1]
	v_mov_b64_e32 v[72:73], v[0:1]
	v_mov_b64_e32 v[76:77], v[0:1]
	v_mov_b64_e32 v[80:81], v[0:1]
	v_mov_b64_e32 v[84:85], v[0:1]
	v_mov_b64_e32 v[88:89], v[0:1]
	v_mov_b64_e32 v[92:93], v[0:1]
	v_mov_b64_e32 v[96:97], v[0:1]
	v_mov_b64_e32 v[100:101], v[0:1]
	v_mov_b64_e32 v[104:105], v[0:1]
	v_mov_b64_e32 v[108:109], v[0:1]
	v_mov_b64_e32 v[112:113], v[0:1]
	v_mov_b64_e32 v[116:117], v[0:1]
	v_mov_b64_e32 v[120:121], v[0:1]
	v_mov_b64_e32 v[124:125], v[0:1]
	s_mov_b32 s78, 0
	s_barrier
	s_branch .LBB0_464

.LBB0_471:
	v_add_u32_e32 v154, s69, v214
	v_add_u32_e32 v230, s69, v233
	v_add_u32_e32 v170, s70, v214
	v_add_u32_e32 v231, s70, v233
	ds_read_b128 v[142:145], v154
	ds_read_b128 v[146:149], v230
	ds_read_b128 v[150:153], v154 offset:2048
	ds_read_b128 v[154:157], v230 offset:2048
	ds_read_b128 v[158:161], v170
	ds_read_b128 v[162:165], v231
	ds_read_b128 v[166:169], v170 offset:2048
	ds_read_b128 v[170:173], v231 offset:2048
	s_add_u32 s46, s4, 0xfff00080
	s_addc_u32 s47, s5, -1
	s_cmp_eq_u32 s85, 28
	s_cselect_b32 s49, s29, s47
	s_cselect_b32 s48, s81, s46
	s_cselect_b32 s47, s27, s84
	s_cselect_b32 s46, s82, s83
	v_lshl_add_u64 v[206:207], s[4:5], 0, v[134:135]
	s_add_i32 m0, s55, 0xc000
	ds_read_b128 v[174:177], v216
	ds_read_b128 v[178:181], v232
	ds_read_b128 v[182:185], v216 offset:2048
	ds_read_b128 v[186:189], v232 offset:2048
	ds_read_b128 v[190:193], v216 offset:4096
	ds_read_b128 v[194:197], v232 offset:4096
	ds_read_b128 v[198:201], v216 offset:6144
	ds_read_b128 v[202:205], v232 offset:6144
	global_load_lds_dwordx4 v[206:207], off
	v_lshl_add_u64 v[206:207], s[4:5], 0, v[136:137]
	s_add_i32 m0, s55, 0xe000
	s_nop 0
	global_load_lds_dwordx4 v[206:207], off
	s_waitcnt vmcnt(8)
	s_waitcnt lgkmcnt(0)
	s_barrier
	s_setprio 1
	s_waitcnt lgkmcnt(0)
	v_mfma_f32_16x16x32_bf16 v[124:127], v[142:145], v[174:177], v[124:127]
	v_mfma_f32_16x16x32_bf16 v[120:123], v[150:153], v[174:177], v[120:123]
	v_mfma_f32_16x16x32_bf16 v[116:119], v[142:145], v[182:185], v[116:119]
	v_mfma_f32_16x16x32_bf16 v[112:115], v[150:153], v[182:185], v[112:115]
	v_mfma_f32_16x16x32_bf16 v[108:111], v[142:145], v[190:193], v[108:111]
	v_mfma_f32_16x16x32_bf16 v[104:107], v[150:153], v[190:193], v[104:107]
	v_mfma_f32_16x16x32_bf16 v[100:103], v[142:145], v[198:201], v[100:103]
	v_mfma_f32_16x16x32_bf16 v[96:99], v[150:153], v[198:201], v[96:99]
	v_mfma_f32_16x16x32_bf16 v[124:127], v[146:149], v[178:181], v[124:127]
	v_mfma_f32_16x16x32_bf16 v[120:123], v[154:157], v[178:181], v[120:123]
	v_mfma_f32_16x16x32_bf16 v[116:119], v[146:149], v[186:189], v[116:119]
	v_mfma_f32_16x16x32_bf16 v[112:115], v[154:157], v[186:189], v[112:115]
	v_mfma_f32_16x16x32_bf16 v[108:111], v[146:149], v[194:197], v[108:111]
	v_mfma_f32_16x16x32_bf16 v[104:107], v[154:157], v[194:197], v[104:107]
	v_mfma_f32_16x16x32_bf16 v[100:103], v[146:149], v[202:205], v[100:103]
	v_mfma_f32_16x16x32_bf16 v[96:99], v[154:157], v[202:205], v[96:99]
	s_setprio 0
	s_setprio 1
	v_mfma_f32_16x16x32_bf16 v[92:95], v[158:161], v[174:177], v[92:95]
	v_mfma_f32_16x16x32_bf16 v[88:91], v[166:169], v[174:177], v[88:91]
	v_mfma_f32_16x16x32_bf16 v[84:87], v[158:161], v[182:185], v[84:87]
	v_mfma_f32_16x16x32_bf16 v[80:83], v[166:169], v[182:185], v[80:83]
	v_mfma_f32_16x16x32_bf16 v[76:79], v[158:161], v[190:193], v[76:79]
	v_mfma_f32_16x16x32_bf16 v[72:75], v[166:169], v[190:193], v[72:75]
	v_mfma_f32_16x16x32_bf16 v[68:71], v[158:161], v[198:201], v[68:71]
	v_mfma_f32_16x16x32_bf16 v[64:67], v[166:169], v[198:201], v[64:67]
	v_mfma_f32_16x16x32_bf16 v[92:95], v[162:165], v[178:181], v[92:95]
	v_mfma_f32_16x16x32_bf16 v[88:91], v[170:173], v[178:181], v[88:91]
	v_mfma_f32_16x16x32_bf16 v[84:87], v[162:165], v[186:189], v[84:87]
	v_mfma_f32_16x16x32_bf16 v[80:83], v[170:173], v[186:189], v[80:83]
	v_mfma_f32_16x16x32_bf16 v[76:79], v[162:165], v[194:197], v[76:79]
	v_mfma_f32_16x16x32_bf16 v[72:75], v[170:173], v[194:197], v[72:75]
	v_mfma_f32_16x16x32_bf16 v[68:71], v[162:165], v[202:205], v[68:71]
	v_mfma_f32_16x16x32_bf16 v[64:67], v[170:173], v[202:205], v[64:67]
	s_setprio 0
	s_barrier
	s_add_i32 s86, s69, s54
	v_lshl_add_u64 v[206:207], s[46:47], 0, v[130:131]
	s_mov_b32 m0, s86
	ds_read_b128 v[174:177], v216 offset:16384
	ds_read_b128 v[178:181], v232 offset:16384
	ds_read_b128 v[182:185], v216 offset:18432
	ds_read_b128 v[186:189], v232 offset:18432
	ds_read_b128 v[190:193], v216 offset:20480
	ds_read_b128 v[194:197], v232 offset:20480
	ds_read_b128 v[198:201], v216 offset:22528
	ds_read_b128 v[202:205], v232 offset:22528
	global_load_lds_dwordx4 v[206:207], off
	s_add_i32 m0, s86, 0x2000
	s_add_u32 s86, s46, 0x100000
	v_lshl_add_u64 v[208:209], s[46:47], 0, v[128:129]
	s_addc_u32 s87, s47, 0
	s_add_i32 s88, s70, s54
	global_load_lds_dwordx4 v[208:209], off
	v_lshl_add_u64 v[210:211], s[86:87], 0, v[130:131]
	s_mov_b32 m0, s88
	v_lshl_add_u64 v[218:219], s[48:49], 0, v[128:129]
	global_load_lds_dwordx4 v[210:211], off
	v_lshl_add_u64 v[210:211], s[86:87], 0, v[128:129]
	s_add_i32 m0, s88, 0x2000
	s_nop 0
	global_load_lds_dwordx4 v[210:211], off
	v_lshl_add_u64 v[210:211], s[48:49], 0, v[130:131]
	s_mov_b32 m0, s55
	s_nop 0
	global_load_lds_dwordx4 v[210:211], off
	s_mov_b32 m0, s56
	s_nop 0
	global_load_lds_dwordx4 v[218:219], off
	s_waitcnt vmcnt(8)
	s_waitcnt lgkmcnt(0)
	s_barrier
	s_setprio 1
	s_waitcnt lgkmcnt(0)
	v_mfma_f32_16x16x32_bf16 v[60:63], v[142:145], v[174:177], v[60:63]
	v_mfma_f32_16x16x32_bf16 v[56:59], v[150:153], v[174:177], v[56:59]
	v_mfma_f32_16x16x32_bf16 v[52:55], v[142:145], v[182:185], v[52:55]
	v_mfma_f32_16x16x32_bf16 v[48:51], v[150:153], v[182:185], v[48:51]
	v_mfma_f32_16x16x32_bf16 v[44:47], v[142:145], v[190:193], v[44:47]
	v_mfma_f32_16x16x32_bf16 v[40:43], v[150:153], v[190:193], v[40:43]
	v_mfma_f32_16x16x32_bf16 v[36:39], v[142:145], v[198:201], v[36:39]
	v_mfma_f32_16x16x32_bf16 v[32:35], v[150:153], v[198:201], v[32:35]
	v_mfma_f32_16x16x32_bf16 v[60:63], v[146:149], v[178:181], v[60:63]
	v_mfma_f32_16x16x32_bf16 v[56:59], v[154:157], v[178:181], v[56:59]
	v_mfma_f32_16x16x32_bf16 v[52:55], v[146:149], v[186:189], v[52:55]
	v_mfma_f32_16x16x32_bf16 v[48:51], v[154:157], v[186:189], v[48:51]
	v_mfma_f32_16x16x32_bf16 v[44:47], v[146:149], v[194:197], v[44:47]
	v_mfma_f32_16x16x32_bf16 v[40:43], v[154:157], v[194:197], v[40:43]
	v_mfma_f32_16x16x32_bf16 v[36:39], v[146:149], v[202:205], v[36:39]
	v_mfma_f32_16x16x32_bf16 v[32:35], v[154:157], v[202:205], v[32:35]
	s_setprio 0
	s_setprio 1
	v_mfma_f32_16x16x32_bf16 v[28:31], v[158:161], v[174:177], v[28:31]
	v_mfma_f32_16x16x32_bf16 v[24:27], v[166:169], v[174:177], v[24:27]
	v_mfma_f32_16x16x32_bf16 v[20:23], v[158:161], v[182:185], v[20:23]
	v_mfma_f32_16x16x32_bf16 v[16:19], v[166:169], v[182:185], v[16:19]
	v_mfma_f32_16x16x32_bf16 v[12:15], v[158:161], v[190:193], v[12:15]
	v_mfma_f32_16x16x32_bf16 v[8:11], v[166:169], v[190:193], v[8:11]
	v_mfma_f32_16x16x32_bf16 v[4:7], v[158:161], v[198:201], v[4:7]
	v_mfma_f32_16x16x32_bf16 v[0:3], v[166:169], v[198:201], v[0:3]
	v_mfma_f32_16x16x32_bf16 v[28:31], v[162:165], v[178:181], v[28:31]
	v_mfma_f32_16x16x32_bf16 v[24:27], v[170:173], v[178:181], v[24:27]
	v_mfma_f32_16x16x32_bf16 v[20:23], v[162:165], v[186:189], v[20:23]
	v_mfma_f32_16x16x32_bf16 v[16:19], v[170:173], v[186:189], v[16:19]
	v_mfma_f32_16x16x32_bf16 v[12:15], v[162:165], v[194:197], v[12:15]
	v_mfma_f32_16x16x32_bf16 v[8:11], v[170:173], v[194:197], v[8:11]
	v_mfma_f32_16x16x32_bf16 v[4:7], v[162:165], v[202:205], v[4:7]
	v_mfma_f32_16x16x32_bf16 v[0:3], v[170:173], v[202:205], v[0:3]
	s_setprio 0
	s_barrier
	s_add_i32 s86, 0, 0x18000
	s_add_i32 s87, 0, 0x1c000
	v_add_u32_e32 v154, s86, v214
	v_add_u32_e32 v230, s86, v233
	v_add_u32_e32 v170, s87, v214
	v_add_u32_e32 v231, s87, v233
	ds_read_b128 v[142:145], v154
	ds_read_b128 v[146:149], v230
	ds_read_b128 v[150:153], v154 offset:2048
	ds_read_b128 v[154:157], v230 offset:2048
	ds_read_b128 v[158:161], v170
	ds_read_b128 v[162:165], v231
	ds_read_b128 v[166:169], v170 offset:2048
	ds_read_b128 v[170:173], v231 offset:2048
	s_add_u32 s48, s48, 0x100000
	s_addc_u32 s49, s49, 0
	s_mov_b32 m0, s57
	v_lshl_add_u64 v[220:221], s[48:49], 0, v[130:131]
	ds_read_b128 v[174:177], v216 offset:32768
	ds_read_b128 v[178:181], v232 offset:32768
	ds_read_b128 v[182:185], v216 offset:34816
	ds_read_b128 v[186:189], v232 offset:34816
	ds_read_b128 v[190:193], v216 offset:36864
	ds_read_b128 v[194:197], v232 offset:36864
	ds_read_b128 v[198:201], v216 offset:38912
	ds_read_b128 v[202:205], v232 offset:38912
	global_load_lds_dwordx4 v[220:221], off
	v_lshl_add_u64 v[220:221], s[48:49], 0, v[128:129]
	s_mov_b32 m0, s58
	s_nop 0
	global_load_lds_dwordx4 v[220:221], off
	s_waitcnt vmcnt(8)
	s_waitcnt lgkmcnt(0)
	s_barrier
	s_setprio 1
	s_waitcnt lgkmcnt(0)
	v_mfma_f32_16x16x32_bf16 v[124:127], v[142:145], v[174:177], v[124:127]
	v_mfma_f32_16x16x32_bf16 v[120:123], v[150:153], v[174:177], v[120:123]
	v_mfma_f32_16x16x32_bf16 v[116:119], v[142:145], v[182:185], v[116:119]
	v_mfma_f32_16x16x32_bf16 v[112:115], v[150:153], v[182:185], v[112:115]
	v_mfma_f32_16x16x32_bf16 v[108:111], v[142:145], v[190:193], v[108:111]
	v_mfma_f32_16x16x32_bf16 v[104:107], v[150:153], v[190:193], v[104:107]
	v_mfma_f32_16x16x32_bf16 v[100:103], v[142:145], v[198:201], v[100:103]
	v_mfma_f32_16x16x32_bf16 v[96:99], v[150:153], v[198:201], v[96:99]
	v_mfma_f32_16x16x32_bf16 v[124:127], v[146:149], v[178:181], v[124:127]
	v_mfma_f32_16x16x32_bf16 v[120:123], v[154:157], v[178:181], v[120:123]
	v_mfma_f32_16x16x32_bf16 v[116:119], v[146:149], v[186:189], v[116:119]
	v_mfma_f32_16x16x32_bf16 v[112:115], v[154:157], v[186:189], v[112:115]
	v_mfma_f32_16x16x32_bf16 v[108:111], v[146:149], v[194:197], v[108:111]
	v_mfma_f32_16x16x32_bf16 v[104:107], v[154:157], v[194:197], v[104:107]
	v_mfma_f32_16x16x32_bf16 v[100:103], v[146:149], v[202:205], v[100:103]
	v_mfma_f32_16x16x32_bf16 v[96:99], v[154:157], v[202:205], v[96:99]
	s_setprio 0
	s_setprio 1
	v_mfma_f32_16x16x32_bf16 v[92:95], v[158:161], v[174:177], v[92:95]
	v_mfma_f32_16x16x32_bf16 v[88:91], v[166:169], v[174:177], v[88:91]
	v_mfma_f32_16x16x32_bf16 v[84:87], v[158:161], v[182:185], v[84:87]
	v_mfma_f32_16x16x32_bf16 v[80:83], v[166:169], v[182:185], v[80:83]
	v_mfma_f32_16x16x32_bf16 v[76:79], v[158:161], v[190:193], v[76:79]
	v_mfma_f32_16x16x32_bf16 v[72:75], v[166:169], v[190:193], v[72:75]
	v_mfma_f32_16x16x32_bf16 v[68:71], v[158:161], v[198:201], v[68:71]
	v_mfma_f32_16x16x32_bf16 v[64:67], v[166:169], v[198:201], v[64:67]
	v_mfma_f32_16x16x32_bf16 v[92:95], v[162:165], v[178:181], v[92:95]
	v_mfma_f32_16x16x32_bf16 v[88:91], v[170:173], v[178:181], v[88:91]
	v_mfma_f32_16x16x32_bf16 v[84:87], v[162:165], v[186:189], v[84:87]
	v_mfma_f32_16x16x32_bf16 v[80:83], v[170:173], v[186:189], v[80:83]
	v_mfma_f32_16x16x32_bf16 v[76:79], v[162:165], v[194:197], v[76:79]
	v_mfma_f32_16x16x32_bf16 v[72:75], v[170:173], v[194:197], v[72:75]
	v_mfma_f32_16x16x32_bf16 v[68:71], v[162:165], v[202:205], v[68:71]
	v_mfma_f32_16x16x32_bf16 v[64:67], v[170:173], v[202:205], v[64:67]
	s_setprio 0
	s_barrier
; template <class Epi, class Sched, bool FP8 = false>
; __device__ __forceinline__ void gemm_phase(LAS unsigned char* lds, const Gemm g, const Sched& S, const Epi& E, const int tid) {
;     ...
;         for (int t = 0; t < nt; t += 2) PG8_KBODY(t);
	s_add_i32 s48, s86, s54
	v_lshl_add_u64 v[206:207], v[206:207], 0, s[14:15]
	s_mov_b32 m0, s48
	ds_read_b128 v[174:177], v216 offset:49152
	ds_read_b128 v[178:181], v232 offset:49152
	ds_read_b128 v[182:185], v216 offset:51200
	ds_read_b128 v[186:189], v232 offset:51200
	ds_read_b128 v[190:193], v216 offset:53248
	ds_read_b128 v[194:197], v232 offset:53248
	ds_read_b128 v[198:201], v216 offset:55296
	ds_read_b128 v[202:205], v232 offset:55296
	global_load_lds_dwordx4 v[206:207], off
	s_add_i32 m0, s48, 0x2000
	s_add_u32 s46, s46, 0x100080
	v_lshl_add_u64 v[206:207], v[208:209], 0, s[14:15]
	s_addc_u32 s47, s47, 0
	s_add_i32 s48, s87, s54
	global_load_lds_dwordx4 v[206:207], off
	v_lshl_add_u64 v[206:207], s[46:47], 0, v[130:131]
	s_mov_b32 m0, s48
	s_nop 0
	global_load_lds_dwordx4 v[206:207], off
	v_lshl_add_u64 v[206:207], s[46:47], 0, v[128:129]
	s_add_i32 m0, s48, 0x2000
	s_nop 0
	global_load_lds_dwordx4 v[206:207], off
	v_lshl_add_u64 v[206:207], v[210:211], 0, s[14:15]
	s_mov_b32 m0, s66
	s_nop 0
	global_load_lds_dwordx4 v[206:207], off
	v_lshl_add_u64 v[206:207], v[218:219], 0, s[14:15]
	s_mov_b32 m0, s68
	s_nop 0
	global_load_lds_dwordx4 v[206:207], off
	s_waitcnt vmcnt(8)
	s_waitcnt lgkmcnt(0)
	s_barrier
	s_setprio 1
	s_waitcnt lgkmcnt(0)
	v_mfma_f32_16x16x32_bf16 v[60:63], v[142:145], v[174:177], v[60:63]
	v_mfma_f32_16x16x32_bf16 v[56:59], v[150:153], v[174:177], v[56:59]
	v_mfma_f32_16x16x32_bf16 v[52:55], v[142:145], v[182:185], v[52:55]
	v_mfma_f32_16x16x32_bf16 v[48:51], v[150:153], v[182:185], v[48:51]
	v_mfma_f32_16x16x32_bf16 v[44:47], v[142:145], v[190:193], v[44:47]
	v_mfma_f32_16x16x32_bf16 v[40:43], v[150:153], v[190:193], v[40:43]
	v_mfma_f32_16x16x32_bf16 v[36:39], v[142:145], v[198:201], v[36:39]
	v_mfma_f32_16x16x32_bf16 v[32:35], v[150:153], v[198:201], v[32:35]
	v_mfma_f32_16x16x32_bf16 v[60:63], v[146:149], v[178:181], v[60:63]
	v_mfma_f32_16x16x32_bf16 v[56:59], v[154:157], v[178:181], v[56:59]
	v_mfma_f32_16x16x32_bf16 v[52:55], v[146:149], v[186:189], v[52:55]
	v_mfma_f32_16x16x32_bf16 v[48:51], v[154:157], v[186:189], v[48:51]
	v_mfma_f32_16x16x32_bf16 v[44:47], v[146:149], v[194:197], v[44:47]
	v_mfma_f32_16x16x32_bf16 v[40:43], v[154:157], v[194:197], v[40:43]
	v_mfma_f32_16x16x32_bf16 v[36:39], v[146:149], v[202:205], v[36:39]
	v_mfma_f32_16x16x32_bf16 v[32:35], v[154:157], v[202:205], v[32:35]
	s_setprio 0
	s_setprio 1
	v_mfma_f32_16x16x32_bf16 v[28:31], v[158:161], v[174:177], v[28:31]
	v_mfma_f32_16x16x32_bf16 v[24:27], v[166:169], v[174:177], v[24:27]
	v_mfma_f32_16x16x32_bf16 v[20:23], v[158:161], v[182:185], v[20:23]
	v_mfma_f32_16x16x32_bf16 v[16:19], v[166:169], v[182:185], v[16:19]
	v_mfma_f32_16x16x32_bf16 v[12:15], v[158:161], v[190:193], v[12:15]
	v_mfma_f32_16x16x32_bf16 v[8:11], v[166:169], v[190:193], v[8:11]
	v_mfma_f32_16x16x32_bf16 v[4:7], v[158:161], v[198:201], v[4:7]
	v_mfma_f32_16x16x32_bf16 v[0:3], v[166:169], v[198:201], v[0:3]
	v_mfma_f32_16x16x32_bf16 v[28:31], v[162:165], v[178:181], v[28:31]
	v_mfma_f32_16x16x32_bf16 v[24:27], v[170:173], v[178:181], v[24:27]
	v_mfma_f32_16x16x32_bf16 v[20:23], v[162:165], v[186:189], v[20:23]
	v_mfma_f32_16x16x32_bf16 v[16:19], v[170:173], v[186:189], v[16:19]
	v_mfma_f32_16x16x32_bf16 v[12:15], v[162:165], v[194:197], v[12:15]
	v_mfma_f32_16x16x32_bf16 v[8:11], v[170:173], v[194:197], v[8:11]
	v_mfma_f32_16x16x32_bf16 v[4:7], v[162:165], v[202:205], v[4:7]
	v_mfma_f32_16x16x32_bf16 v[0:3], v[170:173], v[202:205], v[0:3]
	s_setprio 0
	s_barrier
	s_add_i32 s85, s85, 2
	s_add_u32 s4, s4, 0x100
	s_addc_u32 s5, s5, 0
	s_add_u32 s83, s83, 0x100
	s_addc_u32 s84, s84, 0
	s_cmp_gt_u32 s85, 29
	s_cbranch_scc0 .LBB0_471
	s_and_b64 vcc, exec, s[16:17]
	s_cbranch_vccz .LBB0_474
	s_barrier

; #define fresh_tid() ((wave0 << 6) | lane_id_fresh())
; #define PG8_WAIT_V(n) asm volatile("s_waitcnt vmcnt(" #n ")" ::: "memory")
; #define PG8_BAR __builtin_amdgcn_s_barrier()
; template <class Epi, class Sched, bool FP8 = false>
; __device__ __forceinline__ void gemm_phase(LAS unsigned char* lds, const Gemm g, const Sched& S, const Epi& E, const int tid) {
;     const int wid = __builtin_amdgcn_readfirstlane(tid >> 6), lane = tid & 63, wr = wid >> 2, wc = wid & 3, fr = lane & 15, fq = lane >> 4;
;     const int K = g.K, nt = g.Kloop / BK;
;     const size_t halfb = (size_t)g.Kloop * 2;
;     const int sc8 = 0x7f7f7f7f;
;     unsigned voffA[2];
; #pragma unroll
;     for (int i = 0; i < 2; ++i) { int R, C; stage_rc(tid * 16 + i * 8192, R, C); voffA[i] = (unsigned)(R * K + C) * 2u; }
;     const size_t kstep = (size_t)(BK * 2);
;     const size_t hstep = (size_t)HALF * K * 2;
;     const size_t tstep = 2 * hstep;
;     const unsigned ldsw = (unsigned)wid * 1024u;
;     const int aoff = lds_byte(wr * 64 + fr, fq * 8), boff = lds_byte(wc * 32 + fr, fq * 8);
;     ...
;     Unit cur, nxt; int ui = 0;
;     if (!S.next(0, cur)) return;
;     f32x4 acc[2][2][4][2];
; #pragma unroll
;     for (int a = 0; a < 2; ++a)
; #pragma unroll
;         for (int b = 0; b < 2; ++b)
; #pragma unroll
;             for (int m = 0; m < 4; ++m)
; #pragma unroll
;                 for (int n = 0; n < 2; ++n) acc[a][b][m][n] = (f32x4){0.f, 0.f, 0.f, 0.f};
;     h16x8 At[4][2], B0[2][2], B1[2][2];
;     const char* cA = (const char*)g.A + (size_t)cur.pm * tstep + cur.half * halfb; const char* cB = (const char*)g.Bt + (size_t)cur.pn * tstep + cur.half * halfb;
;     PG8_STAGE(PG8_SB(0, 0), cB); PG8_STAGE(PG8_SB(0, 1), cB + hstep); PG8_STAGE(PG8_SA(0, 0), cA); PG8_STAGE(PG8_SA(0, 1), cA + hstep);
;     if (wr == 1) PG8_BAR;
;     PG8_WAIT_V(2); PG8_BAR;
;     PG8_STAGE(PG8_SB(1, 0), cB + kstep); PG8_STAGE(PG8_SA(1, 0), cA + kstep); PG8_STAGE(PG8_SB(1, 1), cB + hstep + kstep);
;     PG8_WAIT_V(6); PG8_BAR;
; template <int COOP>
; __global__ void __launch_bounds__(512, 2) mega(Args a) {
;     ...
;         pg8::Gemm g{P.MG, P.WOT, T, D, D, D}; pg8::StaticOrder S; S.init(T, D, G, bx, 1, 4);
;         pg8::EpiG3 E{P.x, P.U, P.ssq, P.cnt};
;         pg8::gemm_phase(lds, g, S, E, fresh_tid());
.LBB0_547:
	s_add_u32 s14, s10, 0x10200000
	s_addc_u32 s15, s11, 0
	s_add_u32 s46, s10, 0x14000
	s_addc_u32 s47, s11, 0
	s_and_b64 vcc, exec, s[0:1]
	s_cbranch_vccnz .LBB0_586
	v_ashrrev_i32_e32 v2, 31, v0
	v_lshrrev_b32_e32 v2, 26, v2
	v_lshlrev_b32_e32 v1, 4, v0
	v_add_u32_e32 v2, v0, v2
	v_bfe_i32 v0, v0, 27, 1
	v_lshrrev_b32_e32 v0, 22, v0
	v_add_u32_e32 v0, v1, v0
	v_and_b32_e32 v0, 0xfffffc00, v0
	v_sub_u32_e32 v0, v1, v0
	v_ashrrev_i32_e32 v9, 6, v2
	v_lshrrev_b32_e32 v2, 4, v0
	v_bitop3_b32 v0, v2, v0, 32 bitop3:0x6c
	v_ashrrev_i32_e32 v3, 31, v0
	v_lshrrev_b32_e32 v3, 26, v3
	v_add_u32_e32 v3, v0, v3
	v_ashrrev_i32_e32 v10, 6, v3
	v_and_b32_e32 v3, 0xc0, v3
	v_sub_u32_e32 v0, v0, v3
	v_mov_b32_e32 v3, 1
	v_lshlrev_b32_e32 v2, 3, v9
	v_lshlrev_b32_e32 v4, 5, v9
	v_ashrrev_i16_sdwa v0, v3, sext(v0) dst_sel:DWORD dst_unused:UNUSED_PAD src0_sel:DWORD src1_sel:BYTE_0
	v_and_b32_e32 v2, 0x7fff0, v2
	v_and_b32_e32 v4, 32, v4
	v_bfe_i32 v11, v0, 0, 16
	v_add_u32_e32 v0, v4, v11
	v_add_lshl_u32 v2, v10, v2, 13
	v_lshl_add_u32 v176, v0, 1, v2
	v_mbcnt_lo_u32_b32 v239, -1, 0
	v_mbcnt_hi_u32_b32 v239, -1, v239
	s_lshr_b32 s92, s33, 6
	s_lshl_b32 s93, s92, 3
	s_and_b32 s94, s92, 1
	s_lshl_b32 s94, s94, 2
	v_lshrrev_b32_e32 v236, 3, v239
	v_add_u32_e32 v236, s93, v236
	v_lshrrev_b32_e32 v237, 4, v239
	v_add_u32_e32 v237, s94, v237
	v_and_b32_e32 v238, 7, v239
	v_xor_b32_e32 v237, v238, v237
	v_lshlrev_b32_e32 v237, 4, v237
	v_lshl_add_u32 v176, v236, 13, v237
	v_add_u32_e32 v0, 0x2000, v1
	v_ashrrev_i32_e32 v1, 31, v0
	v_lshrrev_b32_e32 v1, 22, v1
	v_add_u32_e32 v1, v0, v1
	v_ashrrev_i32_e32 v12, 10, v1
	v_mul_i32_i24_e32 v1, 0x400, v12
	v_sub_u32_e32 v0, v0, v1
	v_lshrrev_b32_e32 v1, 4, v0
	s_add_u32 s48, s10, 0xe200000
	v_bitop3_b32 v0, v1, v0, 32 bitop3:0x6c
	s_addc_u32 s49, s11, 0
	v_ashrrev_i32_e32 v2, 31, v0
	s_add_u32 s50, s10, 0x34200000
	v_lshrrev_b32_e32 v2, 26, v2
	s_addc_u32 s51, s11, 0
	v_add_u32_e32 v2, v0, v2
	s_ashr_i32 s1, s6, 6
	s_ashr_i32 s17, s16, 31
	s_ashr_i32 s41, s40, 31
	s_ashr_i32 s0, s6, 8
	v_ashrrev_i32_e32 v13, 6, v2
	v_and_b32_e32 v2, 0xc0, v2
	s_lshl_b32 s52, s1, 10
	s_lshl_b64 s[4:5], s[16:17], 21
	s_lshl_b64 s[18:19], s[40:41], 21
	v_sub_u32_e32 v0, v0, v2
	s_add_u32 s42, s48, s18
	v_lshlrev_b32_e32 v1, 3, v12
	v_lshlrev_b32_e32 v4, 5, v12
	v_ashrrev_i16_sdwa v0, v3, sext(v0) dst_sel:DWORD dst_unused:UNUSED_PAD src0_sel:DWORD src1_sel:BYTE_0
	s_addc_u32 s43, s49, s19
	s_add_i32 s17, s52, 0
	v_and_b32_e32 v1, 0x7fff0, v1
	v_and_b32_e32 v4, 32, v4
	v_bfe_i32 v14, v0, 0, 16
	s_add_i32 m0, s17, 0x10000
	v_add_u32_e32 v0, v4, v14
	v_add_lshl_u32 v1, v13, v1, 13
	global_load_lds_dwordx4 v176, s[42:43]
	s_add_i32 m0, s17, 0x12000
	v_lshl_add_u32 v178, v0, 1, v1
	v_add_u32_e32 v178, 0x80000, v176
	s_add_u32 s18, s42, 0x100000
	global_load_lds_dwordx4 v178, s[42:43]
	s_addc_u32 s19, s43, 0
	s_add_i32 m0, s17, 0x14000
	v_mov_b32_e32 v177, 0
	global_load_lds_dwordx4 v176, s[18:19]
	s_add_i32 m0, s17, 0x16000
	s_add_u32 s38, s50, s4
	s_addc_u32 s39, s51, s5
	s_add_i32 s53, s17, 0x2000
	global_load_lds_dwordx4 v178, s[18:19]
	s_mov_b32 m0, s17
	s_add_u32 s4, s38, 0x100000
	global_load_lds_dwordx4 v176, s[38:39]
	s_mov_b32 m0, s53
	s_addc_u32 s5, s39, 0
	s_add_i32 s54, s17, 0x4000
	global_load_lds_dwordx4 v178, s[38:39]
	s_mov_b32 m0, s54
	s_add_i32 s55, s17, 0x6000
	global_load_lds_dwordx4 v176, s[4:5]
	s_mov_b32 m0, s55
	v_mov_b32_e32 v179, v177
	global_load_lds_dwordx4 v178, s[4:5]
	s_cmp_eq_u32 s0, 1
	s_mov_b32 s56, 0
	v_lshl_add_u64 v[6:7], s[42:43], 0, v[176:177]
	v_lshl_add_u64 v[4:5], s[42:43], 0, v[178:179]
	v_lshl_add_u64 v[0:1], s[38:39], 0, v[176:177]
	s_cselect_b64 s[18:19], -1, 0
	s_cmp_lg_u32 s0, 1
	v_lshl_add_u64 v[2:3], s[38:39], 0, v[178:179]
	s_cbranch_scc1 .LBB0_550
	s_barrier
.LBB0_550:
	s_lshl_b32 s1, s1, 5
	s_mov_b64 s[22:23], 0x80
	s_and_b32 s26, s1, 0x60
	s_add_i32 m0, s17, 0x18000
	v_lshl_add_u64 v[6:7], v[6:7], 0, s[22:23]
	s_lshl_b32 s7, s0, 13
	s_lshl_b32 s1, s26, 7
	s_waitcnt vmcnt(2)
	s_barrier
	global_load_lds_dwordx4 v[6:7], off
	v_lshl_add_u64 v[4:5], v[4:5], 0, s[22:23]
	s_add_i32 m0, s17, 0x1a000
	s_add_i32 s57, s17, 0x8000
	s_add_i32 s58, s17, 0xa000
	global_load_lds_dwordx4 v[4:5], off
	v_lshl_add_u64 v[0:1], v[0:1], 0, s[22:23]
	s_mov_b32 m0, s57
	s_add_u32 s4, s42, 0x100080
	global_load_lds_dwordx4 v[0:1], off
	v_lshl_add_u64 v[0:1], v[2:3], 0, s[22:23]
	s_mov_b32 m0, s58
	s_addc_u32 s5, s43, 0
	global_load_lds_dwordx4 v[0:1], off
	s_add_i32 m0, s17, 0x1c000
	v_lshl_add_u64 v[0:1], s[4:5], 0, v[176:177]
	global_load_lds_dwordx4 v[0:1], off
	v_lshl_add_u64 v[0:1], s[4:5], 0, v[178:179]
	s_add_i32 m0, s17, 0x1e000
	v_lshlrev_b32_e32 v3, 2, v8
	global_load_lds_dwordx4 v[0:1], off
	v_bfe_u32 v1, v8, 4, 2
	v_and_b32_e32 v0, 15, v8
	v_lshlrev_b32_e32 v2, 4, v1
	v_lshl_or_b32 v200, s0, 6, v0
	v_lshl_or_b32 v2, v0, 6, v2
	v_or_b32_e32 v0, v1, v0
	v_cmp_eq_u32_e64 s[4:5], 0, v0
	v_lshlrev_b32_e32 v0, 16, v9
	v_and_b32_e32 v3, 32, v3
	v_and_b32_e32 v0, 0xfffe0000, v0
	v_bitop3_b32 v201, s1, v2, v3 bitop3:0xf6
	v_cmp_eq_u32_e64 s[0:1], 0, v1
	v_lshl_or_b32 v202, v1, 3, s26
	v_lshl_add_u32 v0, v10, 13, v0
	v_and_b32_e32 v1, 1, v9
	v_lshl_or_b32 v0, v1, 6, v0
	v_lshl_add_u32 v180, v11, 1, v0
	v_mov_b32_e32 v180, v176
	v_lshlrev_b32_e32 v0, 16, v12
	v_and_b32_e32 v0, 0xfffe0000, v0
	s_waitcnt vmcnt(6)
	s_cmpk_lt_u32 s6, 0x100
	v_lshl_add_u32 v0, v13, 13, v0
	v_and_b32_e32 v1, 1, v12
	v_bitop3_b32 v4, v2, s7, v3 bitop3:0xde
	s_cselect_b64 s[24:25], -1, 0
	v_lshl_or_b32 v0, v1, 6, v0
	s_add_i32 s59, 0, 0x10000
	s_add_i32 s60, 0, 0x14000
	v_mov_b32_e32 v181, v177
	v_lshl_add_u32 v182, v14, 1, v0
	v_mov_b32_e32 v182, v178
	v_mov_b32_e32 v183, v177
	v_mov_b64_e32 v[184:185], 0x200
	v_mov_b64_e32 v[186:187], 0x1ff
	v_add_u32_e32 v203, s59, v201
	v_add_u32_e32 v204, s60, v201
	v_add_u32_e32 v205, 0, v4
	v_mbcnt_lo_u32_b32 v239, -1, 0
	v_mbcnt_hi_u32_b32 v239, -1, v239
	s_lshr_b32 s92, s33, 6
	s_lshr_b32 s93, s92, 2
	s_lshl_b32 s93, s93, 13
	s_and_b32 s94, s92, 3
	s_lshl_b32 s94, s94, 12
	v_and_b32_e32 v236, 15, v239
	v_lshrrev_b32_e32 v237, 4, v239
	v_lshrrev_b32_e32 v238, 1, v236
	v_xor_b32_e32 v237, v237, v238
	v_lshlrev_b32_e32 v237, 4, v237
	v_lshl_add_u32 v236, v236, 7, v237
	v_add_u32_e32 v205, s93, v236
	v_xor_b32_e32 v232, 64, v205
	v_add_u32_e32 v201, s94, v236
	v_xor_b32_e32 v233, 64, v201
	v_add_u32_e32 v203, 0x10000, v201
	v_add_u32_e32 v234, 0x10000, v233
	v_add_u32_e32 v204, 0x14000, v201
	v_add_u32_e32 v235, 0x14000, v233
	v_mbcnt_hi_u32_b32 v206, -1, v212
	s_barrier
	s_branch .LBB0_553

.LBB0_560:
	ds_read_b128 v[128:131], v203
	ds_read_b128 v[132:135], v234
	ds_read_b128 v[136:139], v203 offset:2048
	ds_read_b128 v[140:143], v234 offset:2048
	ds_read_b128 v[144:147], v204
	ds_read_b128 v[148:151], v235
	ds_read_b128 v[152:155], v204 offset:2048
	ds_read_b128 v[156:159], v235 offset:2048
	s_add_u32 s42, s38, 0xfff00080
	s_addc_u32 s43, s39, -1
	s_cmp_eq_u32 s64, 60
	s_cselect_b32 s45, s29, s43
	s_cselect_b32 s44, s41, s42
	s_cselect_b32 s43, s27, s63
	s_cselect_b32 s42, s61, s62
	v_lshl_add_u64 v[212:213], s[38:39], 0, v[180:181]
	s_add_i32 m0, s17, 0xc000
	ds_read_b128 v[160:163], v205
	ds_read_b128 v[164:167], v232
	ds_read_b128 v[168:171], v205 offset:2048
	ds_read_b128 v[172:175], v232 offset:2048
	ds_read_b128 v[188:191], v205 offset:4096
	ds_read_b128 v[192:195], v232 offset:4096
	ds_read_b128 v[196:199], v205 offset:6144
	ds_read_b128 v[208:211], v232 offset:6144
	global_load_lds_dwordx4 v[212:213], off
	v_lshl_add_u64 v[212:213], s[38:39], 0, v[182:183]
	s_add_i32 m0, s17, 0xe000
	s_nop 0
	global_load_lds_dwordx4 v[212:213], off
	s_waitcnt vmcnt(8)
	s_waitcnt lgkmcnt(0)
	s_barrier
	s_setprio 1
	s_waitcnt lgkmcnt(0)
	v_mfma_f32_16x16x32_bf16 v[124:127], v[128:131], v[160:163], v[124:127]
	v_mfma_f32_16x16x32_bf16 v[120:123], v[136:139], v[160:163], v[120:123]
	v_mfma_f32_16x16x32_bf16 v[108:111], v[128:131], v[168:171], v[108:111]
	v_mfma_f32_16x16x32_bf16 v[104:107], v[136:139], v[168:171], v[104:107]
	v_mfma_f32_16x16x32_bf16 v[92:95], v[128:131], v[188:191], v[92:95]
	v_mfma_f32_16x16x32_bf16 v[88:91], v[136:139], v[188:191], v[88:91]
	v_mfma_f32_16x16x32_bf16 v[76:79], v[128:131], v[196:199], v[76:79]
	v_mfma_f32_16x16x32_bf16 v[72:75], v[136:139], v[196:199], v[72:75]
	v_mfma_f32_16x16x32_bf16 v[124:127], v[132:135], v[164:167], v[124:127]
	v_mfma_f32_16x16x32_bf16 v[120:123], v[140:143], v[164:167], v[120:123]
	v_mfma_f32_16x16x32_bf16 v[108:111], v[132:135], v[172:175], v[108:111]
	v_mfma_f32_16x16x32_bf16 v[104:107], v[140:143], v[172:175], v[104:107]
	v_mfma_f32_16x16x32_bf16 v[92:95], v[132:135], v[192:195], v[92:95]
	v_mfma_f32_16x16x32_bf16 v[88:91], v[140:143], v[192:195], v[88:91]
	v_mfma_f32_16x16x32_bf16 v[76:79], v[132:135], v[208:211], v[76:79]
	v_mfma_f32_16x16x32_bf16 v[72:75], v[140:143], v[208:211], v[72:75]
	s_setprio 0
	s_setprio 1
	v_mfma_f32_16x16x32_bf16 v[116:119], v[144:147], v[160:163], v[116:119]
	v_mfma_f32_16x16x32_bf16 v[112:115], v[152:155], v[160:163], v[112:115]
	v_mfma_f32_16x16x32_bf16 v[100:103], v[144:147], v[168:171], v[100:103]
	v_mfma_f32_16x16x32_bf16 v[96:99], v[152:155], v[168:171], v[96:99]
	v_mfma_f32_16x16x32_bf16 v[84:87], v[144:147], v[188:191], v[84:87]
	v_mfma_f32_16x16x32_bf16 v[80:83], v[152:155], v[188:191], v[80:83]
	v_mfma_f32_16x16x32_bf16 v[68:71], v[144:147], v[196:199], v[68:71]
	v_mfma_f32_16x16x32_bf16 v[64:67], v[152:155], v[196:199], v[64:67]
	v_mfma_f32_16x16x32_bf16 v[116:119], v[148:151], v[164:167], v[116:119]
	v_mfma_f32_16x16x32_bf16 v[112:115], v[156:159], v[164:167], v[112:115]
	v_mfma_f32_16x16x32_bf16 v[100:103], v[148:151], v[172:175], v[100:103]
	v_mfma_f32_16x16x32_bf16 v[96:99], v[156:159], v[172:175], v[96:99]
	v_mfma_f32_16x16x32_bf16 v[84:87], v[148:151], v[192:195], v[84:87]
	v_mfma_f32_16x16x32_bf16 v[80:83], v[156:159], v[192:195], v[80:83]
	v_mfma_f32_16x16x32_bf16 v[68:71], v[148:151], v[208:211], v[68:71]
	v_mfma_f32_16x16x32_bf16 v[64:67], v[156:159], v[208:211], v[64:67]
	s_setprio 0
	s_barrier
	s_add_i32 s65, s59, s52
	v_lshl_add_u64 v[212:213], s[42:43], 0, v[176:177]
	s_mov_b32 m0, s65
	ds_read_b128 v[160:163], v205 offset:16384
	ds_read_b128 v[164:167], v232 offset:16384
	ds_read_b128 v[168:171], v205 offset:18432
	ds_read_b128 v[172:175], v232 offset:18432
	ds_read_b128 v[188:191], v205 offset:20480
	ds_read_b128 v[192:195], v232 offset:20480
	ds_read_b128 v[196:199], v205 offset:22528
	ds_read_b128 v[208:211], v232 offset:22528
	global_load_lds_dwordx4 v[212:213], off
	s_add_i32 m0, s65, 0x2000
	s_add_u32 s66, s42, 0x100000
	v_lshl_add_u64 v[214:215], s[42:43], 0, v[178:179]
	s_addc_u32 s67, s43, 0
	s_add_i32 s65, s60, s52
	global_load_lds_dwordx4 v[214:215], off
	v_lshl_add_u64 v[216:217], s[66:67], 0, v[176:177]
	s_mov_b32 m0, s65
	v_lshl_add_u64 v[218:219], s[44:45], 0, v[178:179]
	global_load_lds_dwordx4 v[216:217], off
	v_lshl_add_u64 v[216:217], s[66:67], 0, v[178:179]
	s_add_i32 m0, s65, 0x2000
	s_nop 0
	global_load_lds_dwordx4 v[216:217], off
	v_lshl_add_u64 v[216:217], s[44:45], 0, v[176:177]
	s_mov_b32 m0, s17
	s_nop 0
	global_load_lds_dwordx4 v[216:217], off
	s_mov_b32 m0, s53
	s_nop 0
	global_load_lds_dwordx4 v[218:219], off
	s_waitcnt vmcnt(8)
	s_waitcnt lgkmcnt(0)
	s_barrier
	s_setprio 1
	s_waitcnt lgkmcnt(0)
	v_mfma_f32_16x16x32_bf16 v[60:63], v[128:131], v[160:163], v[60:63]
	v_mfma_f32_16x16x32_bf16 v[56:59], v[136:139], v[160:163], v[56:59]
	v_mfma_f32_16x16x32_bf16 v[44:47], v[128:131], v[168:171], v[44:47]
	v_mfma_f32_16x16x32_bf16 v[40:43], v[136:139], v[168:171], v[40:43]
	v_mfma_f32_16x16x32_bf16 v[28:31], v[128:131], v[188:191], v[28:31]
	v_mfma_f32_16x16x32_bf16 v[24:27], v[136:139], v[188:191], v[24:27]
	v_mfma_f32_16x16x32_bf16 v[12:15], v[128:131], v[196:199], v[12:15]
	v_mfma_f32_16x16x32_bf16 v[8:11], v[136:139], v[196:199], v[8:11]
	v_mfma_f32_16x16x32_bf16 v[60:63], v[132:135], v[164:167], v[60:63]
	v_mfma_f32_16x16x32_bf16 v[56:59], v[140:143], v[164:167], v[56:59]
	v_mfma_f32_16x16x32_bf16 v[44:47], v[132:135], v[172:175], v[44:47]
	v_mfma_f32_16x16x32_bf16 v[40:43], v[140:143], v[172:175], v[40:43]
	v_mfma_f32_16x16x32_bf16 v[28:31], v[132:135], v[192:195], v[28:31]
	v_mfma_f32_16x16x32_bf16 v[24:27], v[140:143], v[192:195], v[24:27]
	v_mfma_f32_16x16x32_bf16 v[12:15], v[132:135], v[208:211], v[12:15]
	v_mfma_f32_16x16x32_bf16 v[8:11], v[140:143], v[208:211], v[8:11]
	s_setprio 0
	s_setprio 1
	v_mfma_f32_16x16x32_bf16 v[52:55], v[144:147], v[160:163], v[52:55]
	v_mfma_f32_16x16x32_bf16 v[48:51], v[152:155], v[160:163], v[48:51]
	v_mfma_f32_16x16x32_bf16 v[36:39], v[144:147], v[168:171], v[36:39]
	v_mfma_f32_16x16x32_bf16 v[32:35], v[152:155], v[168:171], v[32:35]
	v_mfma_f32_16x16x32_bf16 v[20:23], v[144:147], v[188:191], v[20:23]
	v_mfma_f32_16x16x32_bf16 v[16:19], v[152:155], v[188:191], v[16:19]
	v_mfma_f32_16x16x32_bf16 v[4:7], v[144:147], v[196:199], v[4:7]
	v_mfma_f32_16x16x32_bf16 v[0:3], v[152:155], v[196:199], v[0:3]
	v_mfma_f32_16x16x32_bf16 v[52:55], v[148:151], v[164:167], v[52:55]
	v_mfma_f32_16x16x32_bf16 v[48:51], v[156:159], v[164:167], v[48:51]
	v_mfma_f32_16x16x32_bf16 v[36:39], v[148:151], v[172:175], v[36:39]
	v_mfma_f32_16x16x32_bf16 v[32:35], v[156:159], v[172:175], v[32:35]
	v_mfma_f32_16x16x32_bf16 v[20:23], v[148:151], v[192:195], v[20:23]
	v_mfma_f32_16x16x32_bf16 v[16:19], v[156:159], v[192:195], v[16:19]
	v_mfma_f32_16x16x32_bf16 v[4:7], v[148:151], v[208:211], v[4:7]
	v_mfma_f32_16x16x32_bf16 v[0:3], v[156:159], v[208:211], v[0:3]
	s_setprio 0
	s_barrier
	s_add_i32 s65, 0, 0x18000
	s_add_i32 s66, 0, 0x1c000
	v_add_u32_e32 v140, s65, v201
	v_add_u32_e32 v230, s65, v233
	v_add_u32_e32 v156, s66, v201
	v_add_u32_e32 v231, s66, v233
	ds_read_b128 v[128:131], v140
	ds_read_b128 v[132:135], v230
	ds_read_b128 v[136:139], v140 offset:2048
	ds_read_b128 v[140:143], v230 offset:2048
	ds_read_b128 v[144:147], v156
	ds_read_b128 v[148:151], v231
	ds_read_b128 v[152:155], v156 offset:2048
	ds_read_b128 v[156:159], v231 offset:2048
	s_add_u32 s44, s44, 0x100000
	s_addc_u32 s45, s45, 0
	s_mov_b32 m0, s54
	v_lshl_add_u64 v[220:221], s[44:45], 0, v[176:177]
	ds_read_b128 v[160:163], v205 offset:32768
	ds_read_b128 v[164:167], v232 offset:32768
	ds_read_b128 v[168:171], v205 offset:34816
	ds_read_b128 v[172:175], v232 offset:34816
	ds_read_b128 v[188:191], v205 offset:36864
	ds_read_b128 v[192:195], v232 offset:36864
	ds_read_b128 v[196:199], v205 offset:38912
	ds_read_b128 v[208:211], v232 offset:38912
	global_load_lds_dwordx4 v[220:221], off
	v_lshl_add_u64 v[220:221], s[44:45], 0, v[178:179]
	s_mov_b32 m0, s55
	s_nop 0
	global_load_lds_dwordx4 v[220:221], off
	s_waitcnt vmcnt(8)
	s_waitcnt lgkmcnt(0)
	s_barrier
	s_setprio 1
	s_waitcnt lgkmcnt(0)
	v_mfma_f32_16x16x32_bf16 v[124:127], v[128:131], v[160:163], v[124:127]
	v_mfma_f32_16x16x32_bf16 v[120:123], v[136:139], v[160:163], v[120:123]
	v_mfma_f32_16x16x32_bf16 v[108:111], v[128:131], v[168:171], v[108:111]
	v_mfma_f32_16x16x32_bf16 v[104:107], v[136:139], v[168:171], v[104:107]
	v_mfma_f32_16x16x32_bf16 v[92:95], v[128:131], v[188:191], v[92:95]
	v_mfma_f32_16x16x32_bf16 v[88:91], v[136:139], v[188:191], v[88:91]
	v_mfma_f32_16x16x32_bf16 v[76:79], v[128:131], v[196:199], v[76:79]
	v_mfma_f32_16x16x32_bf16 v[72:75], v[136:139], v[196:199], v[72:75]
	v_mfma_f32_16x16x32_bf16 v[124:127], v[132:135], v[164:167], v[124:127]
	v_mfma_f32_16x16x32_bf16 v[120:123], v[140:143], v[164:167], v[120:123]
	v_mfma_f32_16x16x32_bf16 v[108:111], v[132:135], v[172:175], v[108:111]
	v_mfma_f32_16x16x32_bf16 v[104:107], v[140:143], v[172:175], v[104:107]
	v_mfma_f32_16x16x32_bf16 v[92:95], v[132:135], v[192:195], v[92:95]
	v_mfma_f32_16x16x32_bf16 v[88:91], v[140:143], v[192:195], v[88:91]
	v_mfma_f32_16x16x32_bf16 v[76:79], v[132:135], v[208:211], v[76:79]
	v_mfma_f32_16x16x32_bf16 v[72:75], v[140:143], v[208:211], v[72:75]
	s_setprio 0
	s_setprio 1
	v_mfma_f32_16x16x32_bf16 v[116:119], v[144:147], v[160:163], v[116:119]
	v_mfma_f32_16x16x32_bf16 v[112:115], v[152:155], v[160:163], v[112:115]
	v_mfma_f32_16x16x32_bf16 v[100:103], v[144:147], v[168:171], v[100:103]
	v_mfma_f32_16x16x32_bf16 v[96:99], v[152:155], v[168:171], v[96:99]
	v_mfma_f32_16x16x32_bf16 v[84:87], v[144:147], v[188:191], v[84:87]
	v_mfma_f32_16x16x32_bf16 v[80:83], v[152:155], v[188:191], v[80:83]
	v_mfma_f32_16x16x32_bf16 v[68:71], v[144:147], v[196:199], v[68:71]
	v_mfma_f32_16x16x32_bf16 v[64:67], v[152:155], v[196:199], v[64:67]
	v_mfma_f32_16x16x32_bf16 v[116:119], v[148:151], v[164:167], v[116:119]
	v_mfma_f32_16x16x32_bf16 v[112:115], v[156:159], v[164:167], v[112:115]
	v_mfma_f32_16x16x32_bf16 v[100:103], v[148:151], v[172:175], v[100:103]
	v_mfma_f32_16x16x32_bf16 v[96:99], v[156:159], v[172:175], v[96:99]
	v_mfma_f32_16x16x32_bf16 v[84:87], v[148:151], v[192:195], v[84:87]
	v_mfma_f32_16x16x32_bf16 v[80:83], v[156:159], v[192:195], v[80:83]
	v_mfma_f32_16x16x32_bf16 v[68:71], v[148:151], v[208:211], v[68:71]
	v_mfma_f32_16x16x32_bf16 v[64:67], v[156:159], v[208:211], v[64:67]
	s_setprio 0
	s_barrier
; template <class Epi, class Sched, bool FP8 = false>
; __device__ __forceinline__ void gemm_phase(LAS unsigned char* lds, const Gemm g, const Sched& S, const Epi& E, const int tid) {
;     ...
;         for (int t = 0; t < nt; t += 2) PG8_KBODY(t);
	s_add_i32 s44, s65, s52
	v_lshl_add_u64 v[212:213], v[212:213], 0, s[22:23]
	s_mov_b32 m0, s44
	ds_read_b128 v[160:163], v205 offset:49152
	ds_read_b128 v[164:167], v232 offset:49152
	ds_read_b128 v[168:171], v205 offset:51200
	ds_read_b128 v[172:175], v232 offset:51200
	ds_read_b128 v[188:191], v205 offset:53248
	ds_read_b128 v[192:195], v232 offset:53248
	ds_read_b128 v[196:199], v205 offset:55296
	ds_read_b128 v[208:211], v232 offset:55296
	global_load_lds_dwordx4 v[212:213], off
	s_add_i32 m0, s44, 0x2000
	s_add_u32 s42, s42, 0x100080
	v_lshl_add_u64 v[212:213], v[214:215], 0, s[22:23]
	s_addc_u32 s43, s43, 0
	s_add_i32 s44, s66, s52
	global_load_lds_dwordx4 v[212:213], off
	v_lshl_add_u64 v[212:213], s[42:43], 0, v[176:177]
	s_mov_b32 m0, s44
	s_nop 0
	global_load_lds_dwordx4 v[212:213], off
	v_lshl_add_u64 v[212:213], s[42:43], 0, v[178:179]
	s_add_i32 m0, s44, 0x2000
	s_nop 0
	global_load_lds_dwordx4 v[212:213], off
	v_lshl_add_u64 v[212:213], v[216:217], 0, s[22:23]
	s_mov_b32 m0, s57
	s_nop 0
	global_load_lds_dwordx4 v[212:213], off
	v_lshl_add_u64 v[212:213], v[218:219], 0, s[22:23]
	s_mov_b32 m0, s58
	s_nop 0
	global_load_lds_dwordx4 v[212:213], off
	s_waitcnt vmcnt(8)
	s_waitcnt lgkmcnt(0)
	s_barrier
	s_setprio 1
	s_waitcnt lgkmcnt(0)
	v_mfma_f32_16x16x32_bf16 v[60:63], v[128:131], v[160:163], v[60:63]
	v_mfma_f32_16x16x32_bf16 v[56:59], v[136:139], v[160:163], v[56:59]
	v_mfma_f32_16x16x32_bf16 v[44:47], v[128:131], v[168:171], v[44:47]
	v_mfma_f32_16x16x32_bf16 v[40:43], v[136:139], v[168:171], v[40:43]
	v_mfma_f32_16x16x32_bf16 v[28:31], v[128:131], v[188:191], v[28:31]
	v_mfma_f32_16x16x32_bf16 v[24:27], v[136:139], v[188:191], v[24:27]
	v_mfma_f32_16x16x32_bf16 v[12:15], v[128:131], v[196:199], v[12:15]
	v_mfma_f32_16x16x32_bf16 v[8:11], v[136:139], v[196:199], v[8:11]
	v_mfma_f32_16x16x32_bf16 v[60:63], v[132:135], v[164:167], v[60:63]
	v_mfma_f32_16x16x32_bf16 v[56:59], v[140:143], v[164:167], v[56:59]
	v_mfma_f32_16x16x32_bf16 v[44:47], v[132:135], v[172:175], v[44:47]
	v_mfma_f32_16x16x32_bf16 v[40:43], v[140:143], v[172:175], v[40:43]
	v_mfma_f32_16x16x32_bf16 v[28:31], v[132:135], v[192:195], v[28:31]
	v_mfma_f32_16x16x32_bf16 v[24:27], v[140:143], v[192:195], v[24:27]
	v_mfma_f32_16x16x32_bf16 v[12:15], v[132:135], v[208:211], v[12:15]
	v_mfma_f32_16x16x32_bf16 v[8:11], v[140:143], v[208:211], v[8:11]
	s_setprio 0
	s_setprio 1
	v_mfma_f32_16x16x32_bf16 v[52:55], v[144:147], v[160:163], v[52:55]
	v_mfma_f32_16x16x32_bf16 v[48:51], v[152:155], v[160:163], v[48:51]
	v_mfma_f32_16x16x32_bf16 v[36:39], v[144:147], v[168:171], v[36:39]
	v_mfma_f32_16x16x32_bf16 v[32:35], v[152:155], v[168:171], v[32:35]
	v_mfma_f32_16x16x32_bf16 v[20:23], v[144:147], v[188:191], v[20:23]
	v_mfma_f32_16x16x32_bf16 v[16:19], v[152:155], v[188:191], v[16:19]
	v_mfma_f32_16x16x32_bf16 v[4:7], v[144:147], v[196:199], v[4:7]
	v_mfma_f32_16x16x32_bf16 v[0:3], v[152:155], v[196:199], v[0:3]
	v_mfma_f32_16x16x32_bf16 v[52:55], v[148:151], v[164:167], v[52:55]
	v_mfma_f32_16x16x32_bf16 v[48:51], v[156:159], v[164:167], v[48:51]
	v_mfma_f32_16x16x32_bf16 v[36:39], v[148:151], v[172:175], v[36:39]
	v_mfma_f32_16x16x32_bf16 v[32:35], v[156:159], v[172:175], v[32:35]
	v_mfma_f32_16x16x32_bf16 v[20:23], v[148:151], v[192:195], v[20:23]
	v_mfma_f32_16x16x32_bf16 v[16:19], v[156:159], v[192:195], v[16:19]
	v_mfma_f32_16x16x32_bf16 v[4:7], v[148:151], v[208:211], v[4:7]
	v_mfma_f32_16x16x32_bf16 v[0:3], v[156:159], v[208:211], v[0:3]
	s_setprio 0
	s_barrier
	s_add_i32 s64, s64, 2
	s_add_u32 s38, s38, 0x100
	s_addc_u32 s39, s39, 0
	s_add_u32 s62, s62, 0x100
	s_addc_u32 s63, s63, 0
	s_cmp_gt_u32 s64, 61
	s_cbranch_scc0 .LBB0_560
	s_and_b64 vcc, exec, s[24:25]
	s_cbranch_vccz .LBB0_563
	s_barrier

; template <int COOP>
; __global__ void __launch_bounds__(512, 2) mega(Args a) {
	.amdhsa_kernel _Z4megaILi1EEv4Args
		.amdhsa_group_segment_fixed_size 0
		.amdhsa_private_segment_fixed_size 0
		.amdhsa_kernarg_size 368
		.amdhsa_user_sgpr_count 2
		.amdhsa_user_sgpr_dispatch_ptr 0
		.amdhsa_user_sgpr_queue_ptr 0
		.amdhsa_user_sgpr_kernarg_segment_ptr 1
		.amdhsa_user_sgpr_dispatch_id 0
		.amdhsa_user_sgpr_kernarg_preload_length 0
		.amdhsa_user_sgpr_kernarg_preload_offset 0
		.amdhsa_user_sgpr_private_segment_size 0
		.amdhsa_uses_dynamic_stack 0
		.amdhsa_enable_private_segment 0
		.amdhsa_system_sgpr_workgroup_id_x 1
		.amdhsa_system_sgpr_workgroup_id_y 0
		.amdhsa_system_sgpr_workgroup_id_z 0
		.amdhsa_system_sgpr_workgroup_info 0
		.amdhsa_system_vgpr_workitem_id 2
		.amdhsa_next_free_vgpr 240
		.amdhsa_next_free_sgpr 96
		.amdhsa_accum_offset 240
		.amdhsa_reserve_vcc 1
		.amdhsa_float_round_mode_32 0
		.amdhsa_float_round_mode_16_64 0
		.amdhsa_float_denorm_mode_32 3
		.amdhsa_float_denorm_mode_16_64 3
		.amdhsa_dx10_clamp 1
		.amdhsa_ieee_mode 1
		.amdhsa_fp16_overflow 0
		.amdhsa_tg_split 0
		.amdhsa_exception_fp_ieee_invalid_op 0
		.amdhsa_exception_fp_denorm_src 0
		.amdhsa_exception_fp_ieee_div_zero 0
		.amdhsa_exception_fp_ieee_overflow 0
		.amdhsa_exception_fp_ieee_underflow 0
		.amdhsa_exception_fp_ieee_inexact 0
		.amdhsa_exception_int_div_zero 0
	.end_amdhsa_kernel

; template <int COOP>
; __global__ void __launch_bounds__(512, 2) mega(Args a) {
amdhsa.kernels:
  - .agpr_count:     0
    .args:
      - .offset:         0
        .size:           112
        .value_kind:     by_value
      - .offset:         112
        .size:           4
        .value_kind:     hidden_block_count_x
      - .offset:         116
        .size:           4
        .value_kind:     hidden_block_count_y
      - .offset:         120
        .size:           4
        .value_kind:     hidden_block_count_z
      - .offset:         124
        .size:           2
        .value_kind:     hidden_group_size_x
      - .offset:         126
        .size:           2
        .value_kind:     hidden_group_size_y
      - .offset:         128
        .size:           2
        .value_kind:     hidden_group_size_z
      - .offset:         130
        .size:           2
        .value_kind:     hidden_remainder_x
      - .offset:         132
        .size:           2
        .value_kind:     hidden_remainder_y
      - .offset:         134
        .size:           2
        .value_kind:     hidden_remainder_z
      - .offset:         152
        .size:           8
        .value_kind:     hidden_global_offset_x
      - .offset:         160
        .size:           8
        .value_kind:     hidden_global_offset_y
      - .offset:         168
        .size:           8
        .value_kind:     hidden_global_offset_z
      - .offset:         176
        .size:           2
        .value_kind:     hidden_grid_dims
      - .offset:         200
        .size:           8
        .value_kind:     hidden_multigrid_sync_arg
      - .offset:         232
        .size:           4
        .value_kind:     hidden_dynamic_lds_size
    .group_segment_fixed_size: 0
    .kernarg_segment_align: 8
    .kernarg_segment_size: 368
    .language:       OpenCL C
    .language_version:
      - 2
      - 0
    .max_flat_workgroup_size: 512
    .name:           _Z4megaILi1EEv4Args
    .private_segment_fixed_size: 0
    .sgpr_count:     102
    .sgpr_spill_count: 0
    .symbol:         _Z4megaILi1EEv4Args.kd
    .uniform_work_group_size: 1
    .uses_dynamic_stack: false
    .vgpr_count:     240
    .vgpr_spill_count: 0
    .wavefront_size: 64
